# v86 + QKV and both gelu K-loops: all LDS-DMA loads in SGPR base + lane offset form (no VALU address adds left in any GEMM K-loop)
# speedup vs baseline: 1.0004x; 1.0004x over previous
; #define PG8_STAGE(bufoff, gbase, voff) do { _Pragma("unroll") for (int _i = 0; _i < 2; ++_i) \
;         __builtin_amdgcn_global_load_lds((const unsigned*)((const char*)(gbase) + (voff)[_i]), (PG8_LAS unsigned*)(lds + (bufoff) + ldsw + _i * 8192), 16, 0, 0); } while (0)
; #define PG8_LDA(dst, b, h) do { _Pragma("unroll") for (int m = 0; m < 4; ++m) _Pragma("unroll") for (int k = 0; k < 2; ++k) dst[m][k] = *(const PG8_LAS bf16x8*)(lds + PG8_SA(b, h) + aoff + m * 2048 + k * 1024); } while (0)
; #define PG8_LDB(dst, b, h) do { _Pragma("unroll") for (int n = 0; n < 2; ++n) _Pragma("unroll") for (int k = 0; k < 2; ++k) dst[n][k] = *(const PG8_LAS bf16x8*)(lds + PG8_SB(b, h) + boff + n * 2048 + k * 1024); } while (0)
; #define PG8_MMA(ai, bj, At, Bt) do { __builtin_amdgcn_s_setprio(1); _Pragma("unroll") for (int m = 0; m < 4; ++m) _Pragma("unroll") for (int n = 0; n < 2; ++n) _Pragma("unroll") for (int k = 0; k < 2; ++k) \
;         acc[ai][bj][m][n] = mma16<Epi::I8>(Bt[n][k], At[m][k], acc[ai][bj][m][n]); __builtin_amdgcn_s_setprio(0); } while (0)
; #define PG8_WAIT_V(n) asm volatile("s_waitcnt vmcnt(" #n ")" ::: "memory")
; #define PG8_WAIT_L(n) asm volatile("s_waitcnt lgkmcnt(" #n ")" ::: "memory")
; #define PG8_BAR __builtin_amdgcn_s_barrier()
; template <class Epi, class Sched, bool ALIGN_EPI = false, bool SP2 = false>
; __device__ __forceinline__ void gemm_phase(PG8_LAS unsigned char* lds, const Gemm g, const Sched& S, const Epi& E) {
;     ...
;             const bool last = (t == nt - 2);
;             const char* a1 = cA + (size_t)(t + 1) * kstep;
;             const char* a2 = last ? nA : cA + (size_t)(t + 2) * kstep; const char* b2 = last ? nB : cB + (size_t)(t + 2) * kstep;
;             const char* a3 = a2 + kstep; const char* b3 = b2 + kstep;
;             if (last && has_next) S.a_ready(nxt);
;             if constexpr (SP2) {
;             PG8_LDB(B0, 0, 0); PG8_LDB(B1, 0, 1); PG8_SCHED; PG8_LDA(At, 0, 0); PG8_STAGE(PG8_SA(1, 1), a1 + hstep, voffA);
;             PG8_WAIT_V(8); PG8_WAIT_L(0); PG8_BAR; PG8_MMA(0, 0, At, B0); PG8_MMA(0, 1, At, B1); PG8_BAR; PG8_SCHED;
;             PG8_LDA(At, 0, 1); PG8_STAGE(PG8_SB(0, 0), b2, voffB); PG8_STAGE(PG8_SB(0, 1), b2 + hstep, voffB); PG8_STAGE(PG8_SA(0, 0), a2, voffA);
;             PG8_WAIT_V(8); PG8_WAIT_L(0); PG8_BAR; PG8_MMA(1, 0, At, B0); PG8_MMA(1, 1, At, B1); PG8_BAR; PG8_SCHED;
.Lpeel291:
	s_add_u32 s84, s8, 0x100
	s_addc_u32 s85, s9, 0
	s_add_i32 s66, 0, 0x10000
	s_cmp_eq_u32 s10, 12
	s_cselect_b32 vcc_hi, s5, s85
	s_cselect_b32 vcc_lo, s7, s84
	s_cselect_b32 s97, s11, s68
	s_cselect_b32 s96, s67, s69
	s_add_i32 s70, 0, 0x14000
	v_add_u32_e32 v110, s66, v175
	v_add_u32_e32 v168, s70, v175
	s_waitcnt vmcnt(0)
	ds_read_b128 v[66:69], v110
	ds_read_b128 v[70:73], v110 offset:1024
	ds_read_b128 v[106:109], v110 offset:2048
	ds_read_b128 v[110:113], v110 offset:3072
	ds_read_b128 v[114:117], v168
	ds_read_b128 v[118:121], v168 offset:1024
	ds_read_b128 v[126:129], v168 offset:2048
	ds_read_b128 v[178:181], v168 offset:3072
	s_add_i32 m0, s1, 0xc000
	ds_read_b128 v[182:185], v177
	ds_read_b128 v[186:189], v177 offset:1024
	ds_read_b128 v[190:193], v177 offset:2048
	ds_read_b128 v[194:197], v177 offset:3072
	ds_read_b128 v[198:201], v177 offset:4096
	ds_read_b128 v[210:213], v177 offset:5120
	ds_read_b128 v[214:217], v177 offset:6144
	ds_read_b128 v[218:221], v177 offset:7168
	global_load_lds_dwordx4 v164, s[8:9]
	s_add_i32 m0, s1, 0xe000
	s_nop 0
	global_load_lds_dwordx4 v166, s[8:9]
	s_waitcnt vmcnt(8)
	s_waitcnt lgkmcnt(0)
	s_barrier
	s_waitcnt lgkmcnt(0)
	v_mfma_i32_16x16x64_i8 v[154:157], v[66:69], v[182:185], 0
	v_mfma_i32_16x16x64_i8 v[146:149], v[106:109], v[182:185], 0
	v_mfma_i32_16x16x64_i8 v[138:141], v[106:109], v[190:193], 0
	v_mfma_i32_16x16x64_i8 v[150:153], v[66:69], v[190:193], 0
	v_mfma_i32_16x16x64_i8 v[142:145], v[66:69], v[198:201], 0
	v_mfma_i32_16x16x64_i8 v[130:133], v[106:109], v[198:201], 0
	v_mfma_i32_16x16x64_i8 v[122:125], v[106:109], v[214:217], 0
	v_mfma_i32_16x16x64_i8 v[134:137], v[66:69], v[214:217], 0
	v_mfma_i32_16x16x64_i8 v[154:157], v[70:73], v[186:189], v[154:157]
	v_mfma_i32_16x16x64_i8 v[146:149], v[110:113], v[186:189], v[146:149]
	v_mfma_i32_16x16x64_i8 v[138:141], v[110:113], v[194:197], v[138:141]
	v_mfma_i32_16x16x64_i8 v[150:153], v[70:73], v[194:197], v[150:153]
	v_mfma_i32_16x16x64_i8 v[142:145], v[70:73], v[210:213], v[142:145]
	v_mfma_i32_16x16x64_i8 v[130:133], v[110:113], v[210:213], v[130:133]
	v_mfma_i32_16x16x64_i8 v[122:125], v[110:113], v[218:221], v[122:125]
	v_mfma_i32_16x16x64_i8 v[134:137], v[70:73], v[218:221], v[134:137]
	v_mfma_i32_16x16x64_i8 v[102:105], v[114:117], v[182:185], 0
	v_mfma_i32_16x16x64_i8 v[94:97], v[126:129], v[182:185], 0
	v_mfma_i32_16x16x64_i8 v[86:89], v[126:129], v[190:193], 0
	v_mfma_i32_16x16x64_i8 v[98:101], v[114:117], v[190:193], 0
	v_mfma_i32_16x16x64_i8 v[90:93], v[114:117], v[198:201], 0
	v_mfma_i32_16x16x64_i8 v[78:81], v[126:129], v[198:201], 0
	v_mfma_i32_16x16x64_i8 v[74:77], v[126:129], v[214:217], 0
	v_mfma_i32_16x16x64_i8 v[82:85], v[114:117], v[214:217], 0
	v_mfma_i32_16x16x64_i8 v[102:105], v[118:121], v[186:189], v[102:105]
	v_mfma_i32_16x16x64_i8 v[94:97], v[178:181], v[186:189], v[94:97]
	v_mfma_i32_16x16x64_i8 v[86:89], v[178:181], v[194:197], v[86:89]
	v_mfma_i32_16x16x64_i8 v[98:101], v[118:121], v[194:197], v[98:101]
	v_mfma_i32_16x16x64_i8 v[90:93], v[118:121], v[210:213], v[90:93]
	v_mfma_i32_16x16x64_i8 v[78:81], v[178:181], v[210:213], v[78:81]
	v_mfma_i32_16x16x64_i8 v[74:77], v[178:181], v[218:221], v[74:77]
	v_mfma_i32_16x16x64_i8 v[82:85], v[118:121], v[218:221], v[82:85]
	s_barrier
	s_add_i32 s8, s66, s81
	s_mov_b32 m0, s8
	ds_read_b128 v[182:185], v177 offset:16384
	ds_read_b128 v[186:189], v177 offset:17408
	ds_read_b128 v[190:193], v177 offset:18432
	ds_read_b128 v[194:197], v177 offset:19456
	ds_read_b128 v[198:201], v177 offset:20480
	ds_read_b128 v[210:213], v177 offset:21504
	ds_read_b128 v[214:217], v177 offset:22528
	ds_read_b128 v[218:221], v177 offset:23552
	global_load_lds_dwordx4 v0, s[96:97]
	s_add_i32 m0, s8, 0x2000
	s_add_u32 s8, s96, 0x40000
	s_addc_u32 s9, s97, 0
	s_add_i32 s66, s70, s81
	global_load_lds_dwordx4 v158, s[96:97]
	s_mov_b32 m0, s66
	s_nop 0
	global_load_lds_dwordx4 v0, s[8:9]
	s_add_i32 m0, s66, 0x2000
	s_nop 0
	global_load_lds_dwordx4 v158, s[8:9]
	s_mov_b32 m0, s1
	s_nop 0
	global_load_lds_dwordx4 v162, vcc
	s_mov_b32 m0, s58
	s_nop 0
	global_load_lds_dwordx4 v160, vcc
	s_waitcnt vmcnt(8)
	s_waitcnt lgkmcnt(0)
	s_barrier
	s_waitcnt lgkmcnt(0)
	v_mfma_i32_16x16x64_i8 v[62:65], v[66:69], v[182:185], 0
	v_mfma_i32_16x16x64_i8 v[54:57], v[106:109], v[182:185], 0
	v_mfma_i32_16x16x64_i8 v[46:49], v[106:109], v[190:193], 0
	v_mfma_i32_16x16x64_i8 v[58:61], v[66:69], v[190:193], 0
	v_mfma_i32_16x16x64_i8 v[50:53], v[66:69], v[198:201], 0
	v_mfma_i32_16x16x64_i8 v[38:41], v[106:109], v[198:201], 0
	v_mfma_i32_16x16x64_i8 v[34:37], v[106:109], v[214:217], 0
	v_mfma_i32_16x16x64_i8 v[42:45], v[66:69], v[214:217], 0
	v_mfma_i32_16x16x64_i8 v[62:65], v[70:73], v[186:189], v[62:65]
	v_mfma_i32_16x16x64_i8 v[54:57], v[110:113], v[186:189], v[54:57]
	v_mfma_i32_16x16x64_i8 v[46:49], v[110:113], v[194:197], v[46:49]
	v_mfma_i32_16x16x64_i8 v[58:61], v[70:73], v[194:197], v[58:61]
	v_mfma_i32_16x16x64_i8 v[50:53], v[70:73], v[210:213], v[50:53]
	v_mfma_i32_16x16x64_i8 v[38:41], v[110:113], v[210:213], v[38:41]
	v_mfma_i32_16x16x64_i8 v[34:37], v[110:113], v[218:221], v[34:37]
	v_mfma_i32_16x16x64_i8 v[42:45], v[70:73], v[218:221], v[42:45]
	v_mfma_i32_16x16x64_i8 v[30:33], v[114:117], v[182:185], 0
	v_mfma_i32_16x16x64_i8 v[22:25], v[126:129], v[182:185], 0
	v_mfma_i32_16x16x64_i8 v[14:17], v[126:129], v[190:193], 0
	v_mfma_i32_16x16x64_i8 v[26:29], v[114:117], v[190:193], 0
	v_mfma_i32_16x16x64_i8 v[18:21], v[114:117], v[198:201], 0
	v_mfma_i32_16x16x64_i8 v[6:9], v[126:129], v[198:201], 0
	v_mfma_i32_16x16x64_i8 v[2:5], v[126:129], v[214:217], 0
	v_mfma_i32_16x16x64_i8 v[10:13], v[114:117], v[214:217], 0
	v_mfma_i32_16x16x64_i8 v[30:33], v[118:121], v[186:189], v[30:33]
	v_mfma_i32_16x16x64_i8 v[22:25], v[178:181], v[186:189], v[22:25]
	v_mfma_i32_16x16x64_i8 v[14:17], v[178:181], v[194:197], v[14:17]
	v_mfma_i32_16x16x64_i8 v[26:29], v[118:121], v[194:197], v[26:29]
	v_mfma_i32_16x16x64_i8 v[18:21], v[118:121], v[210:213], v[18:21]
	v_mfma_i32_16x16x64_i8 v[6:9], v[178:181], v[210:213], v[6:9]
	v_mfma_i32_16x16x64_i8 v[2:5], v[178:181], v[218:221], v[2:5]
	v_mfma_i32_16x16x64_i8 v[10:13], v[118:121], v[218:221], v[10:13]
	s_barrier
; #define PG8_STAGE(bufoff, gbase, voff) do { _Pragma("unroll") for (int _i = 0; _i < 2; ++_i) \
;         __builtin_amdgcn_global_load_lds((const unsigned*)((const char*)(gbase) + (voff)[_i]), (PG8_LAS unsigned*)(lds + (bufoff) + ldsw + _i * 8192), 16, 0, 0); } while (0)
; #define PG8_LDA(dst, b, h) do { _Pragma("unroll") for (int m = 0; m < 4; ++m) _Pragma("unroll") for (int k = 0; k < 2; ++k) dst[m][k] = *(const PG8_LAS bf16x8*)(lds + PG8_SA(b, h) + aoff + m * 2048 + k * 1024); } while (0)
; #define PG8_LDB(dst, b, h) do { _Pragma("unroll") for (int n = 0; n < 2; ++n) _Pragma("unroll") for (int k = 0; k < 2; ++k) dst[n][k] = *(const PG8_LAS bf16x8*)(lds + PG8_SB(b, h) + boff + n * 2048 + k * 1024); } while (0)
; #define PG8_MMA(ai, bj, At, Bt) do { __builtin_amdgcn_s_setprio(1); _Pragma("unroll") for (int m = 0; m < 4; ++m) _Pragma("unroll") for (int n = 0; n < 2; ++n) _Pragma("unroll") for (int k = 0; k < 2; ++k) \
;         acc[ai][bj][m][n] = mma16<Epi::I8>(Bt[n][k], At[m][k], acc[ai][bj][m][n]); __builtin_amdgcn_s_setprio(0); } while (0)
; #define PG8_WAIT_V(n) asm volatile("s_waitcnt vmcnt(" #n ")" ::: "memory")
; #define PG8_WAIT_L(n) asm volatile("s_waitcnt lgkmcnt(" #n ")" ::: "memory")
; #define PG8_BAR __builtin_amdgcn_s_barrier()
; #define PG8_SCHED __builtin_amdgcn_sched_barrier(0)
; template <class Epi, class Sched, bool ALIGN_EPI = false, bool SP2 = false>
; __device__ __forceinline__ void gemm_phase(PG8_LAS unsigned char* lds, const Gemm g, const Sched& S, const Epi& E) {
;     ...
;         for (int t = 0; t < nt; t += 2) {
;     ...
;             PG8_LDB(B0, 1, 0); PG8_LDB(B1, 1, 1); PG8_SCHED; PG8_LDA(At, 1, 0); PG8_STAGE(PG8_SA(0, 1), a2 + hstep, voffA);
;             PG8_WAIT_V(8); PG8_WAIT_L(0); PG8_BAR; PG8_MMA(0, 0, At, B0); PG8_MMA(0, 1, At, B1); PG8_BAR; PG8_SCHED;
;             PG8_LDA(At, 1, 1); PG8_STAGE(PG8_SB(1, 0), b3, voffB); PG8_STAGE(PG8_SB(1, 1), b3 + hstep, voffB); PG8_STAGE(PG8_SA(1, 0), a3, voffA);
;             PG8_WAIT_V(8); PG8_WAIT_L(0); PG8_BAR; PG8_MMA(1, 0, At, B0); PG8_MMA(1, 1, At, B1); PG8_BAR; PG8_SCHED;
	s_add_i32 s66, 0, 0x18000
	s_add_i32 s70, 0, 0x1c000
	v_add_u32_e32 v110, s66, v175
	v_add_u32_e32 v170, s70, v175
	ds_read_b128 v[66:69], v110
	ds_read_b128 v[70:73], v110 offset:1024
	ds_read_b128 v[106:109], v110 offset:2048
	ds_read_b128 v[110:113], v110 offset:3072
	ds_read_b128 v[114:117], v170
	ds_read_b128 v[118:121], v170 offset:1024
	ds_read_b128 v[126:129], v170 offset:2048
	ds_read_b128 v[178:181], v170 offset:3072
	s_add_u32 s8, vcc_lo, 0x40000
	s_addc_u32 s9, vcc_hi, 0
	s_mov_b32 m0, s80
	ds_read_b128 v[182:185], v177 offset:32768
	ds_read_b128 v[186:189], v177 offset:33792
	ds_read_b128 v[190:193], v177 offset:34816
	ds_read_b128 v[194:197], v177 offset:35840
	ds_read_b128 v[198:201], v177 offset:36864
	ds_read_b128 v[210:213], v177 offset:37888
	ds_read_b128 v[214:217], v177 offset:38912
	ds_read_b128 v[218:221], v177 offset:39936
	global_load_lds_dwordx4 v162, s[8:9]
	s_mov_b32 m0, s0
	s_nop 0
	global_load_lds_dwordx4 v160, s[8:9]
	s_waitcnt vmcnt(8)
	s_waitcnt lgkmcnt(0)
	s_barrier
	s_waitcnt lgkmcnt(0)
	v_mfma_i32_16x16x64_i8 v[154:157], v[66:69], v[182:185], v[154:157]
	v_mfma_i32_16x16x64_i8 v[146:149], v[106:109], v[182:185], v[146:149]
	v_mfma_i32_16x16x64_i8 v[138:141], v[106:109], v[190:193], v[138:141]
	v_mfma_i32_16x16x64_i8 v[150:153], v[66:69], v[190:193], v[150:153]
	v_mfma_i32_16x16x64_i8 v[142:145], v[66:69], v[198:201], v[142:145]
	v_mfma_i32_16x16x64_i8 v[130:133], v[106:109], v[198:201], v[130:133]
	v_mfma_i32_16x16x64_i8 v[122:125], v[106:109], v[214:217], v[122:125]
	v_mfma_i32_16x16x64_i8 v[134:137], v[66:69], v[214:217], v[134:137]
	v_mfma_i32_16x16x64_i8 v[154:157], v[70:73], v[186:189], v[154:157]
	v_mfma_i32_16x16x64_i8 v[146:149], v[110:113], v[186:189], v[146:149]
	v_mfma_i32_16x16x64_i8 v[138:141], v[110:113], v[194:197], v[138:141]
	v_mfma_i32_16x16x64_i8 v[150:153], v[70:73], v[194:197], v[150:153]
	v_mfma_i32_16x16x64_i8 v[142:145], v[70:73], v[210:213], v[142:145]
	v_mfma_i32_16x16x64_i8 v[130:133], v[110:113], v[210:213], v[130:133]
	v_mfma_i32_16x16x64_i8 v[122:125], v[110:113], v[218:221], v[122:125]
	v_mfma_i32_16x16x64_i8 v[134:137], v[70:73], v[218:221], v[134:137]
	v_mfma_i32_16x16x64_i8 v[102:105], v[114:117], v[182:185], v[102:105]
	v_mfma_i32_16x16x64_i8 v[94:97], v[126:129], v[182:185], v[94:97]
	v_mfma_i32_16x16x64_i8 v[86:89], v[126:129], v[190:193], v[86:89]
	v_mfma_i32_16x16x64_i8 v[98:101], v[114:117], v[190:193], v[98:101]
	v_mfma_i32_16x16x64_i8 v[90:93], v[114:117], v[198:201], v[90:93]
	v_mfma_i32_16x16x64_i8 v[78:81], v[126:129], v[198:201], v[78:81]
	v_mfma_i32_16x16x64_i8 v[74:77], v[126:129], v[214:217], v[74:77]
	v_mfma_i32_16x16x64_i8 v[82:85], v[114:117], v[214:217], v[82:85]
	v_mfma_i32_16x16x64_i8 v[102:105], v[118:121], v[186:189], v[102:105]
	v_mfma_i32_16x16x64_i8 v[94:97], v[178:181], v[186:189], v[94:97]
	v_mfma_i32_16x16x64_i8 v[86:89], v[178:181], v[194:197], v[86:89]
	v_mfma_i32_16x16x64_i8 v[98:101], v[118:121], v[194:197], v[98:101]
	v_mfma_i32_16x16x64_i8 v[90:93], v[118:121], v[210:213], v[90:93]
	v_mfma_i32_16x16x64_i8 v[78:81], v[178:181], v[210:213], v[78:81]
	v_mfma_i32_16x16x64_i8 v[74:77], v[178:181], v[218:221], v[74:77]
	v_mfma_i32_16x16x64_i8 v[82:85], v[118:121], v[218:221], v[82:85]
	s_barrier
	s_add_i32 s8, s66, s81
	s_add_u32 s98, s96, 0x80
	s_addc_u32 s99, s97, 0
	s_add_u32 s100, vcc_lo, 0x80
	s_addc_u32 s101, vcc_hi, 0
	s_mov_b32 m0, s8
	ds_read_b128 v[182:185], v177 offset:49152
	ds_read_b128 v[186:189], v177 offset:50176
	ds_read_b128 v[190:193], v177 offset:51200
	ds_read_b128 v[194:197], v177 offset:52224
	ds_read_b128 v[198:201], v177 offset:53248
	ds_read_b128 v[210:213], v177 offset:54272
	ds_read_b128 v[214:217], v177 offset:55296
	ds_read_b128 v[218:221], v177 offset:56320
	global_load_lds_dwordx4 v0, s[98:99]
	s_add_i32 m0, s8, 0x2000
	s_add_u32 s8, s96, 0x40080
	s_addc_u32 s9, s97, 0
	s_add_i32 s66, s70, s81
	global_load_lds_dwordx4 v158, s[98:99]
	s_mov_b32 m0, s66
	s_nop 0
	global_load_lds_dwordx4 v0, s[8:9]
	s_add_i32 m0, s66, 0x2000
	s_nop 0
	global_load_lds_dwordx4 v158, s[8:9]
	s_mov_b32 m0, s13
	s_nop 0
	global_load_lds_dwordx4 v162, s[100:101]
	s_mov_b32 m0, s12
	s_nop 0
	global_load_lds_dwordx4 v160, s[100:101]
	s_waitcnt vmcnt(8)
	s_waitcnt lgkmcnt(0)
	s_barrier
	s_waitcnt lgkmcnt(0)
	v_mfma_i32_16x16x64_i8 v[62:65], v[66:69], v[182:185], v[62:65]
	v_mfma_i32_16x16x64_i8 v[54:57], v[106:109], v[182:185], v[54:57]
	v_mfma_i32_16x16x64_i8 v[46:49], v[106:109], v[190:193], v[46:49]
	v_mfma_i32_16x16x64_i8 v[58:61], v[66:69], v[190:193], v[58:61]
	v_mfma_i32_16x16x64_i8 v[50:53], v[66:69], v[198:201], v[50:53]
	v_mfma_i32_16x16x64_i8 v[38:41], v[106:109], v[198:201], v[38:41]
	v_mfma_i32_16x16x64_i8 v[34:37], v[106:109], v[214:217], v[34:37]
	v_mfma_i32_16x16x64_i8 v[42:45], v[66:69], v[214:217], v[42:45]
	v_mfma_i32_16x16x64_i8 v[62:65], v[70:73], v[186:189], v[62:65]
	v_mfma_i32_16x16x64_i8 v[54:57], v[110:113], v[186:189], v[54:57]
	v_mfma_i32_16x16x64_i8 v[46:49], v[110:113], v[194:197], v[46:49]
	v_mfma_i32_16x16x64_i8 v[58:61], v[70:73], v[194:197], v[58:61]
	v_mfma_i32_16x16x64_i8 v[50:53], v[70:73], v[210:213], v[50:53]
	v_mfma_i32_16x16x64_i8 v[38:41], v[110:113], v[210:213], v[38:41]
	v_mfma_i32_16x16x64_i8 v[34:37], v[110:113], v[218:221], v[34:37]
	v_mfma_i32_16x16x64_i8 v[42:45], v[70:73], v[218:221], v[42:45]
	v_mfma_i32_16x16x64_i8 v[30:33], v[114:117], v[182:185], v[30:33]
	v_mfma_i32_16x16x64_i8 v[22:25], v[126:129], v[182:185], v[22:25]
	v_mfma_i32_16x16x64_i8 v[14:17], v[126:129], v[190:193], v[14:17]
	v_mfma_i32_16x16x64_i8 v[26:29], v[114:117], v[190:193], v[26:29]
	v_mfma_i32_16x16x64_i8 v[18:21], v[114:117], v[198:201], v[18:21]
	v_mfma_i32_16x16x64_i8 v[6:9], v[126:129], v[198:201], v[6:9]
	v_mfma_i32_16x16x64_i8 v[2:5], v[126:129], v[214:217], v[2:5]
	v_mfma_i32_16x16x64_i8 v[10:13], v[114:117], v[214:217], v[10:13]
	v_mfma_i32_16x16x64_i8 v[30:33], v[118:121], v[186:189], v[30:33]
	v_mfma_i32_16x16x64_i8 v[22:25], v[178:181], v[186:189], v[22:25]
	v_mfma_i32_16x16x64_i8 v[14:17], v[178:181], v[194:197], v[14:17]
	v_mfma_i32_16x16x64_i8 v[26:29], v[118:121], v[194:197], v[26:29]
	v_mfma_i32_16x16x64_i8 v[18:21], v[118:121], v[210:213], v[18:21]
	v_mfma_i32_16x16x64_i8 v[6:9], v[178:181], v[210:213], v[6:9]
	v_mfma_i32_16x16x64_i8 v[2:5], v[178:181], v[218:221], v[2:5]
	v_mfma_i32_16x16x64_i8 v[10:13], v[118:121], v[218:221], v[10:13]
	s_barrier
	s_add_i32 s10, s10, 2
	s_add_u32 s69, s69, 0x100
	s_addc_u32 s68, s68, 0
	s_cmp_gt_u32 s10, 13
	s_mov_b64 s[8:9], s[84:85]
	s_cbranch_scc0 .LBB0_291
	s_branch .Lpeelx291
; #define PG8_STAGE(bufoff, gbase, voff) do { _Pragma("unroll") for (int _i = 0; _i < 2; ++_i) \
;         __builtin_amdgcn_global_load_lds((const unsigned*)((const char*)(gbase) + (voff)[_i]), (PG8_LAS unsigned*)(lds + (bufoff) + ldsw + _i * 8192), 16, 0, 0); } while (0)
; #define PG8_LDA(dst, b, h) do { _Pragma("unroll") for (int m = 0; m < 4; ++m) _Pragma("unroll") for (int k = 0; k < 2; ++k) dst[m][k] = *(const PG8_LAS bf16x8*)(lds + PG8_SA(b, h) + aoff + m * 2048 + k * 1024); } while (0)
; #define PG8_LDB(dst, b, h) do { _Pragma("unroll") for (int n = 0; n < 2; ++n) _Pragma("unroll") for (int k = 0; k < 2; ++k) dst[n][k] = *(const PG8_LAS bf16x8*)(lds + PG8_SB(b, h) + boff + n * 2048 + k * 1024); } while (0)
; #define PG8_MMA(ai, bj, At, Bt) do { __builtin_amdgcn_s_setprio(1); _Pragma("unroll") for (int m = 0; m < 4; ++m) _Pragma("unroll") for (int n = 0; n < 2; ++n) _Pragma("unroll") for (int k = 0; k < 2; ++k) \
;         acc[ai][bj][m][n] = mma16<Epi::I8>(Bt[n][k], At[m][k], acc[ai][bj][m][n]); __builtin_amdgcn_s_setprio(0); } while (0)
; #define PG8_WAIT_V(n) asm volatile("s_waitcnt vmcnt(" #n ")" ::: "memory")
; #define PG8_WAIT_L(n) asm volatile("s_waitcnt lgkmcnt(" #n ")" ::: "memory")
; #define PG8_BAR __builtin_amdgcn_s_barrier()
; template <class Epi, class Sched, bool ALIGN_EPI = false, bool SP2 = false>
; __device__ __forceinline__ void gemm_phase(PG8_LAS unsigned char* lds, const Gemm g, const Sched& S, const Epi& E) {
;     ...
;             const bool last = (t == nt - 2);
;             const char* a1 = cA + (size_t)(t + 1) * kstep;
;             const char* a2 = last ? nA : cA + (size_t)(t + 2) * kstep; const char* b2 = last ? nB : cB + (size_t)(t + 2) * kstep;
;             const char* a3 = a2 + kstep; const char* b3 = b2 + kstep;
;             if (last && has_next) S.a_ready(nxt);
;             if constexpr (SP2) {
;             PG8_LDB(B0, 0, 0); PG8_LDB(B1, 0, 1); PG8_SCHED; PG8_LDA(At, 0, 0); PG8_STAGE(PG8_SA(1, 1), a1 + hstep, voffA);
;             PG8_WAIT_V(8); PG8_WAIT_L(0); PG8_BAR; PG8_MMA(0, 0, At, B0); PG8_MMA(0, 1, At, B1); PG8_BAR; PG8_SCHED;
;             PG8_LDA(At, 0, 1); PG8_STAGE(PG8_SB(0, 0), b2, voffB); PG8_STAGE(PG8_SB(0, 1), b2 + hstep, voffB); PG8_STAGE(PG8_SA(0, 0), a2, voffA);
;             PG8_WAIT_V(8); PG8_WAIT_L(0); PG8_BAR; PG8_MMA(1, 0, At, B0); PG8_MMA(1, 1, At, B1); PG8_BAR; PG8_SCHED;
.LBB0_291:
	s_add_u32 s84, s8, 0x100
	s_addc_u32 s85, s9, 0
	s_add_i32 s66, 0, 0x10000
	s_cmp_eq_u32 s10, 12
	s_cselect_b32 vcc_hi, s5, s85
	s_cselect_b32 vcc_lo, s7, s84
	s_cselect_b32 s97, s11, s68
	s_cselect_b32 s96, s67, s69
	s_add_i32 s70, 0, 0x14000
	v_add_u32_e32 v110, s66, v175
	v_add_u32_e32 v168, s70, v175
	s_waitcnt vmcnt(0)
	ds_read_b128 v[66:69], v110
	ds_read_b128 v[70:73], v110 offset:1024
	ds_read_b128 v[106:109], v110 offset:2048
	ds_read_b128 v[110:113], v110 offset:3072
	ds_read_b128 v[114:117], v168
	ds_read_b128 v[118:121], v168 offset:1024
	ds_read_b128 v[126:129], v168 offset:2048
	ds_read_b128 v[178:181], v168 offset:3072
	s_add_i32 m0, s1, 0xc000
	ds_read_b128 v[182:185], v177
	ds_read_b128 v[186:189], v177 offset:1024
	ds_read_b128 v[190:193], v177 offset:2048
	ds_read_b128 v[194:197], v177 offset:3072
	ds_read_b128 v[198:201], v177 offset:4096
	ds_read_b128 v[210:213], v177 offset:5120
	ds_read_b128 v[214:217], v177 offset:6144
	ds_read_b128 v[218:221], v177 offset:7168
	global_load_lds_dwordx4 v164, s[8:9]
	s_add_i32 m0, s1, 0xe000
	s_nop 0
	global_load_lds_dwordx4 v166, s[8:9]
	s_waitcnt vmcnt(8)
	s_waitcnt lgkmcnt(0)
	s_barrier
	s_waitcnt lgkmcnt(0)
	v_mfma_i32_16x16x64_i8 v[154:157], v[66:69], v[182:185], v[154:157]
	v_mfma_i32_16x16x64_i8 v[146:149], v[106:109], v[182:185], v[146:149]
	v_mfma_i32_16x16x64_i8 v[138:141], v[106:109], v[190:193], v[138:141]
	v_mfma_i32_16x16x64_i8 v[150:153], v[66:69], v[190:193], v[150:153]
	v_mfma_i32_16x16x64_i8 v[142:145], v[66:69], v[198:201], v[142:145]
	v_mfma_i32_16x16x64_i8 v[130:133], v[106:109], v[198:201], v[130:133]
	v_mfma_i32_16x16x64_i8 v[122:125], v[106:109], v[214:217], v[122:125]
	v_mfma_i32_16x16x64_i8 v[134:137], v[66:69], v[214:217], v[134:137]
	v_mfma_i32_16x16x64_i8 v[154:157], v[70:73], v[186:189], v[154:157]
	v_mfma_i32_16x16x64_i8 v[146:149], v[110:113], v[186:189], v[146:149]
	v_mfma_i32_16x16x64_i8 v[138:141], v[110:113], v[194:197], v[138:141]
	v_mfma_i32_16x16x64_i8 v[150:153], v[70:73], v[194:197], v[150:153]
	v_mfma_i32_16x16x64_i8 v[142:145], v[70:73], v[210:213], v[142:145]
	v_mfma_i32_16x16x64_i8 v[130:133], v[110:113], v[210:213], v[130:133]
	v_mfma_i32_16x16x64_i8 v[122:125], v[110:113], v[218:221], v[122:125]
	v_mfma_i32_16x16x64_i8 v[134:137], v[70:73], v[218:221], v[134:137]
	v_mfma_i32_16x16x64_i8 v[102:105], v[114:117], v[182:185], v[102:105]
	v_mfma_i32_16x16x64_i8 v[94:97], v[126:129], v[182:185], v[94:97]
	v_mfma_i32_16x16x64_i8 v[86:89], v[126:129], v[190:193], v[86:89]
	v_mfma_i32_16x16x64_i8 v[98:101], v[114:117], v[190:193], v[98:101]
	v_mfma_i32_16x16x64_i8 v[90:93], v[114:117], v[198:201], v[90:93]
	v_mfma_i32_16x16x64_i8 v[78:81], v[126:129], v[198:201], v[78:81]
	v_mfma_i32_16x16x64_i8 v[74:77], v[126:129], v[214:217], v[74:77]
	v_mfma_i32_16x16x64_i8 v[82:85], v[114:117], v[214:217], v[82:85]
	v_mfma_i32_16x16x64_i8 v[102:105], v[118:121], v[186:189], v[102:105]
	v_mfma_i32_16x16x64_i8 v[94:97], v[178:181], v[186:189], v[94:97]
	v_mfma_i32_16x16x64_i8 v[86:89], v[178:181], v[194:197], v[86:89]
	v_mfma_i32_16x16x64_i8 v[98:101], v[118:121], v[194:197], v[98:101]
	v_mfma_i32_16x16x64_i8 v[90:93], v[118:121], v[210:213], v[90:93]
	v_mfma_i32_16x16x64_i8 v[78:81], v[178:181], v[210:213], v[78:81]
	v_mfma_i32_16x16x64_i8 v[74:77], v[178:181], v[218:221], v[74:77]
	v_mfma_i32_16x16x64_i8 v[82:85], v[118:121], v[218:221], v[82:85]
	s_barrier
	s_add_i32 s8, s66, s81
	s_mov_b32 m0, s8
	ds_read_b128 v[182:185], v177 offset:16384
	ds_read_b128 v[186:189], v177 offset:17408
	ds_read_b128 v[190:193], v177 offset:18432
	ds_read_b128 v[194:197], v177 offset:19456
	ds_read_b128 v[198:201], v177 offset:20480
	ds_read_b128 v[210:213], v177 offset:21504
	ds_read_b128 v[214:217], v177 offset:22528
	ds_read_b128 v[218:221], v177 offset:23552
	global_load_lds_dwordx4 v0, s[96:97]
	s_add_i32 m0, s8, 0x2000
	s_add_u32 s8, s96, 0x40000
	s_addc_u32 s9, s97, 0
	s_add_i32 s66, s70, s81
	global_load_lds_dwordx4 v158, s[96:97]
	s_mov_b32 m0, s66
	s_nop 0
	global_load_lds_dwordx4 v0, s[8:9]
	s_add_i32 m0, s66, 0x2000
	s_nop 0
	global_load_lds_dwordx4 v158, s[8:9]
	s_mov_b32 m0, s1
	s_nop 0
	global_load_lds_dwordx4 v162, vcc
	s_mov_b32 m0, s58
	s_nop 0
	global_load_lds_dwordx4 v160, vcc
	s_waitcnt vmcnt(8)
	s_waitcnt lgkmcnt(0)
	s_barrier
	s_waitcnt lgkmcnt(0)
	v_mfma_i32_16x16x64_i8 v[62:65], v[66:69], v[182:185], v[62:65]
	v_mfma_i32_16x16x64_i8 v[54:57], v[106:109], v[182:185], v[54:57]
	v_mfma_i32_16x16x64_i8 v[46:49], v[106:109], v[190:193], v[46:49]
	v_mfma_i32_16x16x64_i8 v[58:61], v[66:69], v[190:193], v[58:61]
	v_mfma_i32_16x16x64_i8 v[50:53], v[66:69], v[198:201], v[50:53]
	v_mfma_i32_16x16x64_i8 v[38:41], v[106:109], v[198:201], v[38:41]
	v_mfma_i32_16x16x64_i8 v[34:37], v[106:109], v[214:217], v[34:37]
	v_mfma_i32_16x16x64_i8 v[42:45], v[66:69], v[214:217], v[42:45]
	v_mfma_i32_16x16x64_i8 v[62:65], v[70:73], v[186:189], v[62:65]
	v_mfma_i32_16x16x64_i8 v[54:57], v[110:113], v[186:189], v[54:57]
	v_mfma_i32_16x16x64_i8 v[46:49], v[110:113], v[194:197], v[46:49]
	v_mfma_i32_16x16x64_i8 v[58:61], v[70:73], v[194:197], v[58:61]
	v_mfma_i32_16x16x64_i8 v[50:53], v[70:73], v[210:213], v[50:53]
	v_mfma_i32_16x16x64_i8 v[38:41], v[110:113], v[210:213], v[38:41]
	v_mfma_i32_16x16x64_i8 v[34:37], v[110:113], v[218:221], v[34:37]
	v_mfma_i32_16x16x64_i8 v[42:45], v[70:73], v[218:221], v[42:45]
	v_mfma_i32_16x16x64_i8 v[30:33], v[114:117], v[182:185], v[30:33]
	v_mfma_i32_16x16x64_i8 v[22:25], v[126:129], v[182:185], v[22:25]
	v_mfma_i32_16x16x64_i8 v[14:17], v[126:129], v[190:193], v[14:17]
	v_mfma_i32_16x16x64_i8 v[26:29], v[114:117], v[190:193], v[26:29]
	v_mfma_i32_16x16x64_i8 v[18:21], v[114:117], v[198:201], v[18:21]
	v_mfma_i32_16x16x64_i8 v[6:9], v[126:129], v[198:201], v[6:9]
	v_mfma_i32_16x16x64_i8 v[2:5], v[126:129], v[214:217], v[2:5]
	v_mfma_i32_16x16x64_i8 v[10:13], v[114:117], v[214:217], v[10:13]
	v_mfma_i32_16x16x64_i8 v[30:33], v[118:121], v[186:189], v[30:33]
	v_mfma_i32_16x16x64_i8 v[22:25], v[178:181], v[186:189], v[22:25]
	v_mfma_i32_16x16x64_i8 v[14:17], v[178:181], v[194:197], v[14:17]
	v_mfma_i32_16x16x64_i8 v[26:29], v[118:121], v[194:197], v[26:29]
	v_mfma_i32_16x16x64_i8 v[18:21], v[118:121], v[210:213], v[18:21]
	v_mfma_i32_16x16x64_i8 v[6:9], v[178:181], v[210:213], v[6:9]
	v_mfma_i32_16x16x64_i8 v[2:5], v[178:181], v[218:221], v[2:5]
	v_mfma_i32_16x16x64_i8 v[10:13], v[118:121], v[218:221], v[10:13]
	s_barrier
; #define PG8_STAGE(bufoff, gbase, voff) do { _Pragma("unroll") for (int _i = 0; _i < 2; ++_i) \
;         __builtin_amdgcn_global_load_lds((const unsigned*)((const char*)(gbase) + (voff)[_i]), (PG8_LAS unsigned*)(lds + (bufoff) + ldsw + _i * 8192), 16, 0, 0); } while (0)
; #define PG8_LDA(dst, b, h) do { _Pragma("unroll") for (int m = 0; m < 4; ++m) _Pragma("unroll") for (int k = 0; k < 2; ++k) dst[m][k] = *(const PG8_LAS bf16x8*)(lds + PG8_SA(b, h) + aoff + m * 2048 + k * 1024); } while (0)
; #define PG8_LDB(dst, b, h) do { _Pragma("unroll") for (int n = 0; n < 2; ++n) _Pragma("unroll") for (int k = 0; k < 2; ++k) dst[n][k] = *(const PG8_LAS bf16x8*)(lds + PG8_SB(b, h) + boff + n * 2048 + k * 1024); } while (0)
; #define PG8_MMA(ai, bj, At, Bt) do { __builtin_amdgcn_s_setprio(1); _Pragma("unroll") for (int m = 0; m < 4; ++m) _Pragma("unroll") for (int n = 0; n < 2; ++n) _Pragma("unroll") for (int k = 0; k < 2; ++k) \
;         acc[ai][bj][m][n] = mma16<Epi::I8>(Bt[n][k], At[m][k], acc[ai][bj][m][n]); __builtin_amdgcn_s_setprio(0); } while (0)
; #define PG8_WAIT_V(n) asm volatile("s_waitcnt vmcnt(" #n ")" ::: "memory")
; #define PG8_WAIT_L(n) asm volatile("s_waitcnt lgkmcnt(" #n ")" ::: "memory")
; #define PG8_BAR __builtin_amdgcn_s_barrier()
; #define PG8_SCHED __builtin_amdgcn_sched_barrier(0)
; template <class Epi, class Sched, bool ALIGN_EPI = false, bool SP2 = false>
; __device__ __forceinline__ void gemm_phase(PG8_LAS unsigned char* lds, const Gemm g, const Sched& S, const Epi& E) {
;     ...
;         for (int t = 0; t < nt; t += 2) {
;     ...
;             PG8_LDB(B0, 1, 0); PG8_LDB(B1, 1, 1); PG8_SCHED; PG8_LDA(At, 1, 0); PG8_STAGE(PG8_SA(0, 1), a2 + hstep, voffA);
;             PG8_WAIT_V(8); PG8_WAIT_L(0); PG8_BAR; PG8_MMA(0, 0, At, B0); PG8_MMA(0, 1, At, B1); PG8_BAR; PG8_SCHED;
;             PG8_LDA(At, 1, 1); PG8_STAGE(PG8_SB(1, 0), b3, voffB); PG8_STAGE(PG8_SB(1, 1), b3 + hstep, voffB); PG8_STAGE(PG8_SA(1, 0), a3, voffA);
;             PG8_WAIT_V(8); PG8_WAIT_L(0); PG8_BAR; PG8_MMA(1, 0, At, B0); PG8_MMA(1, 1, At, B1); PG8_BAR; PG8_SCHED;
	s_add_i32 s66, 0, 0x18000
	s_add_i32 s70, 0, 0x1c000
	v_add_u32_e32 v110, s66, v175
	v_add_u32_e32 v170, s70, v175
	ds_read_b128 v[66:69], v110
	ds_read_b128 v[70:73], v110 offset:1024
	ds_read_b128 v[106:109], v110 offset:2048
	ds_read_b128 v[110:113], v110 offset:3072
	ds_read_b128 v[114:117], v170
	ds_read_b128 v[118:121], v170 offset:1024
	ds_read_b128 v[126:129], v170 offset:2048
	ds_read_b128 v[178:181], v170 offset:3072
	s_add_u32 s8, vcc_lo, 0x40000
	s_addc_u32 s9, vcc_hi, 0
	s_mov_b32 m0, s80
	ds_read_b128 v[182:185], v177 offset:32768
	ds_read_b128 v[186:189], v177 offset:33792
	ds_read_b128 v[190:193], v177 offset:34816
	ds_read_b128 v[194:197], v177 offset:35840
	ds_read_b128 v[198:201], v177 offset:36864
	ds_read_b128 v[210:213], v177 offset:37888
	ds_read_b128 v[214:217], v177 offset:38912
	ds_read_b128 v[218:221], v177 offset:39936
	global_load_lds_dwordx4 v162, s[8:9]
	s_mov_b32 m0, s0
	s_nop 0
	global_load_lds_dwordx4 v160, s[8:9]
	s_waitcnt vmcnt(8)
	s_waitcnt lgkmcnt(0)
	s_barrier
	s_waitcnt lgkmcnt(0)
	v_mfma_i32_16x16x64_i8 v[154:157], v[66:69], v[182:185], v[154:157]
	v_mfma_i32_16x16x64_i8 v[146:149], v[106:109], v[182:185], v[146:149]
	v_mfma_i32_16x16x64_i8 v[138:141], v[106:109], v[190:193], v[138:141]
	v_mfma_i32_16x16x64_i8 v[150:153], v[66:69], v[190:193], v[150:153]
	v_mfma_i32_16x16x64_i8 v[142:145], v[66:69], v[198:201], v[142:145]
	v_mfma_i32_16x16x64_i8 v[130:133], v[106:109], v[198:201], v[130:133]
	v_mfma_i32_16x16x64_i8 v[122:125], v[106:109], v[214:217], v[122:125]
	v_mfma_i32_16x16x64_i8 v[134:137], v[66:69], v[214:217], v[134:137]
	v_mfma_i32_16x16x64_i8 v[154:157], v[70:73], v[186:189], v[154:157]
	v_mfma_i32_16x16x64_i8 v[146:149], v[110:113], v[186:189], v[146:149]
	v_mfma_i32_16x16x64_i8 v[138:141], v[110:113], v[194:197], v[138:141]
	v_mfma_i32_16x16x64_i8 v[150:153], v[70:73], v[194:197], v[150:153]
	v_mfma_i32_16x16x64_i8 v[142:145], v[70:73], v[210:213], v[142:145]
	v_mfma_i32_16x16x64_i8 v[130:133], v[110:113], v[210:213], v[130:133]
	v_mfma_i32_16x16x64_i8 v[122:125], v[110:113], v[218:221], v[122:125]
	v_mfma_i32_16x16x64_i8 v[134:137], v[70:73], v[218:221], v[134:137]
	v_mfma_i32_16x16x64_i8 v[102:105], v[114:117], v[182:185], v[102:105]
	v_mfma_i32_16x16x64_i8 v[94:97], v[126:129], v[182:185], v[94:97]
	v_mfma_i32_16x16x64_i8 v[86:89], v[126:129], v[190:193], v[86:89]
	v_mfma_i32_16x16x64_i8 v[98:101], v[114:117], v[190:193], v[98:101]
	v_mfma_i32_16x16x64_i8 v[90:93], v[114:117], v[198:201], v[90:93]
	v_mfma_i32_16x16x64_i8 v[78:81], v[126:129], v[198:201], v[78:81]
	v_mfma_i32_16x16x64_i8 v[74:77], v[126:129], v[214:217], v[74:77]
	v_mfma_i32_16x16x64_i8 v[82:85], v[114:117], v[214:217], v[82:85]
	v_mfma_i32_16x16x64_i8 v[102:105], v[118:121], v[186:189], v[102:105]
	v_mfma_i32_16x16x64_i8 v[94:97], v[178:181], v[186:189], v[94:97]
	v_mfma_i32_16x16x64_i8 v[86:89], v[178:181], v[194:197], v[86:89]
	v_mfma_i32_16x16x64_i8 v[98:101], v[118:121], v[194:197], v[98:101]
	v_mfma_i32_16x16x64_i8 v[90:93], v[118:121], v[210:213], v[90:93]
	v_mfma_i32_16x16x64_i8 v[78:81], v[178:181], v[210:213], v[78:81]
	v_mfma_i32_16x16x64_i8 v[74:77], v[178:181], v[218:221], v[74:77]
	v_mfma_i32_16x16x64_i8 v[82:85], v[118:121], v[218:221], v[82:85]
	s_barrier
	s_add_i32 s8, s66, s81
	s_add_u32 s98, s96, 0x80
	s_addc_u32 s99, s97, 0
	s_add_u32 s100, vcc_lo, 0x80
	s_addc_u32 s101, vcc_hi, 0
	s_mov_b32 m0, s8
	ds_read_b128 v[182:185], v177 offset:49152
	ds_read_b128 v[186:189], v177 offset:50176
	ds_read_b128 v[190:193], v177 offset:51200
	ds_read_b128 v[194:197], v177 offset:52224
	ds_read_b128 v[198:201], v177 offset:53248
	ds_read_b128 v[210:213], v177 offset:54272
	ds_read_b128 v[214:217], v177 offset:55296
	ds_read_b128 v[218:221], v177 offset:56320
	global_load_lds_dwordx4 v0, s[98:99]
	s_add_i32 m0, s8, 0x2000
	s_add_u32 s8, s96, 0x40080
	s_addc_u32 s9, s97, 0
	s_add_i32 s66, s70, s81
	global_load_lds_dwordx4 v158, s[98:99]
	s_mov_b32 m0, s66
	s_nop 0
	global_load_lds_dwordx4 v0, s[8:9]
	s_add_i32 m0, s66, 0x2000
	s_nop 0
	global_load_lds_dwordx4 v158, s[8:9]
	s_mov_b32 m0, s13
	s_nop 0
	global_load_lds_dwordx4 v162, s[100:101]
	s_mov_b32 m0, s12
	s_nop 0
	global_load_lds_dwordx4 v160, s[100:101]
	s_waitcnt vmcnt(8)
	s_waitcnt lgkmcnt(0)
	s_barrier
	s_waitcnt lgkmcnt(0)
	v_mfma_i32_16x16x64_i8 v[62:65], v[66:69], v[182:185], v[62:65]
	v_mfma_i32_16x16x64_i8 v[54:57], v[106:109], v[182:185], v[54:57]
	v_mfma_i32_16x16x64_i8 v[46:49], v[106:109], v[190:193], v[46:49]
	v_mfma_i32_16x16x64_i8 v[58:61], v[66:69], v[190:193], v[58:61]
	v_mfma_i32_16x16x64_i8 v[50:53], v[66:69], v[198:201], v[50:53]
	v_mfma_i32_16x16x64_i8 v[38:41], v[106:109], v[198:201], v[38:41]
	v_mfma_i32_16x16x64_i8 v[34:37], v[106:109], v[214:217], v[34:37]
	v_mfma_i32_16x16x64_i8 v[42:45], v[66:69], v[214:217], v[42:45]
	v_mfma_i32_16x16x64_i8 v[62:65], v[70:73], v[186:189], v[62:65]
	v_mfma_i32_16x16x64_i8 v[54:57], v[110:113], v[186:189], v[54:57]
	v_mfma_i32_16x16x64_i8 v[46:49], v[110:113], v[194:197], v[46:49]
	v_mfma_i32_16x16x64_i8 v[58:61], v[70:73], v[194:197], v[58:61]
	v_mfma_i32_16x16x64_i8 v[50:53], v[70:73], v[210:213], v[50:53]
	v_mfma_i32_16x16x64_i8 v[38:41], v[110:113], v[210:213], v[38:41]
	v_mfma_i32_16x16x64_i8 v[34:37], v[110:113], v[218:221], v[34:37]
	v_mfma_i32_16x16x64_i8 v[42:45], v[70:73], v[218:221], v[42:45]
	v_mfma_i32_16x16x64_i8 v[30:33], v[114:117], v[182:185], v[30:33]
	v_mfma_i32_16x16x64_i8 v[22:25], v[126:129], v[182:185], v[22:25]
	v_mfma_i32_16x16x64_i8 v[14:17], v[126:129], v[190:193], v[14:17]
	v_mfma_i32_16x16x64_i8 v[26:29], v[114:117], v[190:193], v[26:29]
	v_mfma_i32_16x16x64_i8 v[18:21], v[114:117], v[198:201], v[18:21]
	v_mfma_i32_16x16x64_i8 v[6:9], v[126:129], v[198:201], v[6:9]
	v_mfma_i32_16x16x64_i8 v[2:5], v[126:129], v[214:217], v[2:5]
	v_mfma_i32_16x16x64_i8 v[10:13], v[114:117], v[214:217], v[10:13]
	v_mfma_i32_16x16x64_i8 v[30:33], v[118:121], v[186:189], v[30:33]
	v_mfma_i32_16x16x64_i8 v[22:25], v[178:181], v[186:189], v[22:25]
	v_mfma_i32_16x16x64_i8 v[14:17], v[178:181], v[194:197], v[14:17]
	v_mfma_i32_16x16x64_i8 v[26:29], v[118:121], v[194:197], v[26:29]
	v_mfma_i32_16x16x64_i8 v[18:21], v[118:121], v[210:213], v[18:21]
	v_mfma_i32_16x16x64_i8 v[6:9], v[178:181], v[210:213], v[6:9]
	v_mfma_i32_16x16x64_i8 v[2:5], v[178:181], v[218:221], v[2:5]
	v_mfma_i32_16x16x64_i8 v[10:13], v[118:121], v[218:221], v[10:13]
	s_barrier
	s_add_i32 s10, s10, 2
	s_add_u32 s69, s69, 0x100
	s_addc_u32 s68, s68, 0
	s_cmp_gt_u32 s10, 13
	s_mov_b64 s[8:9], s[84:85]
	s_cbranch_scc0 .LBB0_291

; #define PG8_STAGE(bufoff, gbase, voff) do { _Pragma("unroll") for (int _i = 0; _i < 2; ++_i) \
;         __builtin_amdgcn_global_load_lds((const unsigned*)((const char*)(gbase) + (voff)[_i]), (PG8_LAS unsigned*)(lds + (bufoff) + ldsw + _i * 8192), 16, 0, 0); } while (0)
; #define PG8_LDA(dst, b, h) do { _Pragma("unroll") for (int m = 0; m < 4; ++m) _Pragma("unroll") for (int k = 0; k < 2; ++k) dst[m][k] = *(const PG8_LAS bf16x8*)(lds + PG8_SA(b, h) + aoff + m * 2048 + k * 1024); } while (0)
; #define PG8_LDB(dst, b, h) do { _Pragma("unroll") for (int n = 0; n < 2; ++n) _Pragma("unroll") for (int k = 0; k < 2; ++k) dst[n][k] = *(const PG8_LAS bf16x8*)(lds + PG8_SB(b, h) + boff + n * 2048 + k * 1024); } while (0)
; #define PG8_MMA(ai, bj, At, Bt) do { __builtin_amdgcn_s_setprio(1); _Pragma("unroll") for (int m = 0; m < 4; ++m) _Pragma("unroll") for (int n = 0; n < 2; ++n) _Pragma("unroll") for (int k = 0; k < 2; ++k) \
;         acc[ai][bj][m][n] = mma16<Epi::I8>(Bt[n][k], At[m][k], acc[ai][bj][m][n]); __builtin_amdgcn_s_setprio(0); } while (0)
; #define PG8_WAIT_V(n) asm volatile("s_waitcnt vmcnt(" #n ")" ::: "memory")
; #define PG8_WAIT_L(n) asm volatile("s_waitcnt lgkmcnt(" #n ")" ::: "memory")
; #define PG8_BAR __builtin_amdgcn_s_barrier()
; template <class Epi, class Sched, bool ALIGN_EPI = false, bool SP2 = false>
; __device__ __forceinline__ void gemm_phase(PG8_LAS unsigned char* lds, const Gemm g, const Sched& S, const Epi& E) {
;     ...
;             const bool last = (t == nt - 2);
;             const char* a1 = cA + (size_t)(t + 1) * kstep;
;             const char* a2 = last ? nA : cA + (size_t)(t + 2) * kstep; const char* b2 = last ? nB : cB + (size_t)(t + 2) * kstep;
;             const char* a3 = a2 + kstep; const char* b3 = b2 + kstep;
;             if (last && has_next) S.a_ready(nxt);
;             if constexpr (SP2) {
;             PG8_LDB(B0, 0, 0); PG8_LDB(B1, 0, 1); PG8_SCHED; PG8_LDA(At, 0, 0); PG8_STAGE(PG8_SA(1, 1), a1 + hstep, voffA);
;             PG8_WAIT_V(8); PG8_WAIT_L(0); PG8_BAR; PG8_MMA(0, 0, At, B0); PG8_MMA(0, 1, At, B1); PG8_BAR; PG8_SCHED;
;             PG8_LDA(At, 0, 1); PG8_STAGE(PG8_SB(0, 0), b2, voffB); PG8_STAGE(PG8_SB(0, 1), b2 + hstep, voffB); PG8_STAGE(PG8_SA(0, 0), a2, voffA);
;             PG8_WAIT_V(8); PG8_WAIT_L(0); PG8_BAR; PG8_MMA(1, 0, At, B0); PG8_MMA(1, 1, At, B1); PG8_BAR; PG8_SCHED;
.Lpeel327:
	s_add_u32 s68, s8, 0x100
	s_addc_u32 s69, s9, 0
	s_add_i32 s84, 0, 0x10000
	s_cmp_eq_u32 s4, 28
	s_cselect_b32 vcc_hi, s1, s69
	s_cselect_b32 vcc_lo, s5, s68
	v_add_u32_e32 v0, s84, v188
	s_cselect_b32 s71, s7, s96
	s_cselect_b32 s70, s85, s97
	s_add_i32 s10, 0, 0x14000
	ds_read_b128 v[52:55], v0
	ds_read_b128 v[56:59], v0 offset:1024
	ds_read_b128 v[76:79], v0 offset:2048
	ds_read_b128 v[80:83], v0 offset:3072
	v_add_u32_e32 v0, s10, v188
	ds_read_b128 v[116:119], v0
	ds_read_b128 v[120:123], v0 offset:1024
	ds_read_b128 v[168:171], v0 offset:2048
	ds_read_b128 v[172:175], v0 offset:3072
	s_add_i32 m0, s58, 0xc000
	ds_read_b128 v[176:179], v189
	ds_read_b128 v[180:183], v189 offset:1024
	ds_read_b128 v[190:193], v189 offset:2048
	ds_read_b128 v[194:197], v189 offset:3072
	ds_read_b128 v[198:201], v189 offset:4096
	ds_read_b128 v[210:213], v189 offset:5120
	ds_read_b128 v[214:217], v189 offset:6144
	ds_read_b128 v[218:221], v189 offset:7168
	global_load_lds_dwordx4 v164, s[8:9]
	s_add_i32 m0, s58, 0xe000
	s_nop 0
	global_load_lds_dwordx4 v166, s[8:9]
	s_waitcnt vmcnt(8)
	s_waitcnt lgkmcnt(0)
	s_barrier
	s_waitcnt lgkmcnt(0)
	v_mfma_f32_16x16x32_bf16 v[152:155], v[52:55], v[176:179], 0
	v_mfma_f32_16x16x32_bf16 v[144:147], v[76:79], v[176:179], 0
	v_mfma_f32_16x16x32_bf16 v[140:143], v[76:79], v[190:193], 0
	v_mfma_f32_16x16x32_bf16 v[148:151], v[52:55], v[190:193], 0
	v_mfma_f32_16x16x32_bf16 v[136:139], v[52:55], v[198:201], 0
	v_mfma_f32_16x16x32_bf16 v[132:135], v[76:79], v[198:201], 0
	v_mfma_f32_16x16x32_bf16 v[124:127], v[76:79], v[214:217], 0
	v_mfma_f32_16x16x32_bf16 v[128:131], v[52:55], v[214:217], 0
	v_mfma_f32_16x16x32_bf16 v[152:155], v[56:59], v[180:183], v[152:155]
	v_mfma_f32_16x16x32_bf16 v[144:147], v[80:83], v[180:183], v[144:147]
	v_mfma_f32_16x16x32_bf16 v[140:143], v[80:83], v[194:197], v[140:143]
	v_mfma_f32_16x16x32_bf16 v[148:151], v[56:59], v[194:197], v[148:151]
	v_mfma_f32_16x16x32_bf16 v[136:139], v[56:59], v[210:213], v[136:139]
	v_mfma_f32_16x16x32_bf16 v[132:135], v[80:83], v[210:213], v[132:135]
	v_mfma_f32_16x16x32_bf16 v[124:127], v[80:83], v[218:221], v[124:127]
	v_mfma_f32_16x16x32_bf16 v[128:131], v[56:59], v[218:221], v[128:131]
	v_mfma_f32_16x16x32_bf16 v[112:115], v[116:119], v[176:179], 0
	v_mfma_f32_16x16x32_bf16 v[104:107], v[168:171], v[176:179], 0
	v_mfma_f32_16x16x32_bf16 v[100:103], v[168:171], v[190:193], 0
	v_mfma_f32_16x16x32_bf16 v[108:111], v[116:119], v[190:193], 0
	v_mfma_f32_16x16x32_bf16 v[96:99], v[116:119], v[198:201], 0
	v_mfma_f32_16x16x32_bf16 v[92:95], v[168:171], v[198:201], 0
	v_mfma_f32_16x16x32_bf16 v[84:87], v[168:171], v[214:217], 0
	v_mfma_f32_16x16x32_bf16 v[88:91], v[116:119], v[214:217], 0
	v_mfma_f32_16x16x32_bf16 v[112:115], v[120:123], v[180:183], v[112:115]
	v_mfma_f32_16x16x32_bf16 v[104:107], v[172:175], v[180:183], v[104:107]
	v_mfma_f32_16x16x32_bf16 v[100:103], v[172:175], v[194:197], v[100:103]
	v_mfma_f32_16x16x32_bf16 v[108:111], v[120:123], v[194:197], v[108:111]
	v_mfma_f32_16x16x32_bf16 v[96:99], v[120:123], v[210:213], v[96:99]
	v_mfma_f32_16x16x32_bf16 v[92:95], v[172:175], v[210:213], v[92:95]
	v_mfma_f32_16x16x32_bf16 v[84:87], v[172:175], v[218:221], v[84:87]
	v_mfma_f32_16x16x32_bf16 v[88:91], v[120:123], v[218:221], v[88:91]
	s_barrier
	s_add_i32 s8, s84, s80
	s_mov_b32 m0, s8
	ds_read_b128 v[176:179], v189 offset:16384
	ds_read_b128 v[180:183], v189 offset:17408
	ds_read_b128 v[190:193], v189 offset:18432
	ds_read_b128 v[194:197], v189 offset:19456
	ds_read_b128 v[198:201], v189 offset:20480
	ds_read_b128 v[210:213], v189 offset:21504
	ds_read_b128 v[214:217], v189 offset:22528
	ds_read_b128 v[218:221], v189 offset:23552
	global_load_lds_dwordx4 v158, s[70:71]
	s_add_i32 m0, s8, 0x2000
	s_add_u32 s8, s70, 0x80000
	s_addc_u32 s9, s71, 0
	s_add_i32 s10, s10, s80
	global_load_lds_dwordx4 v162, s[70:71]
	s_mov_b32 m0, s10
	s_nop 0
	global_load_lds_dwordx4 v158, s[8:9]
	s_add_i32 m0, s10, 0x2000
	s_nop 0
	global_load_lds_dwordx4 v162, s[8:9]
	s_mov_b32 m0, s58
	s_nop 0
	global_load_lds_dwordx4 v156, vcc
	s_mov_b32 m0, s12
	s_nop 0
	global_load_lds_dwordx4 v160, vcc
	s_waitcnt vmcnt(8)
	s_waitcnt lgkmcnt(0)
	s_barrier
	s_waitcnt lgkmcnt(0)
	v_mfma_f32_16x16x32_bf16 v[72:75], v[52:55], v[176:179], 0
	v_mfma_f32_16x16x32_bf16 v[64:67], v[76:79], v[176:179], 0
	v_mfma_f32_16x16x32_bf16 v[60:63], v[76:79], v[190:193], 0
	v_mfma_f32_16x16x32_bf16 v[68:71], v[52:55], v[190:193], 0
	v_mfma_f32_16x16x32_bf16 v[48:51], v[52:55], v[198:201], 0
	v_mfma_f32_16x16x32_bf16 v[44:47], v[76:79], v[198:201], 0
	v_mfma_f32_16x16x32_bf16 v[36:39], v[76:79], v[214:217], 0
	v_mfma_f32_16x16x32_bf16 v[40:43], v[52:55], v[214:217], 0
	v_mfma_f32_16x16x32_bf16 v[72:75], v[56:59], v[180:183], v[72:75]
	v_mfma_f32_16x16x32_bf16 v[64:67], v[80:83], v[180:183], v[64:67]
	v_mfma_f32_16x16x32_bf16 v[60:63], v[80:83], v[194:197], v[60:63]
	v_mfma_f32_16x16x32_bf16 v[68:71], v[56:59], v[194:197], v[68:71]
	v_mfma_f32_16x16x32_bf16 v[48:51], v[56:59], v[210:213], v[48:51]
	v_mfma_f32_16x16x32_bf16 v[44:47], v[80:83], v[210:213], v[44:47]
	v_mfma_f32_16x16x32_bf16 v[36:39], v[80:83], v[218:221], v[36:39]
	v_mfma_f32_16x16x32_bf16 v[40:43], v[56:59], v[218:221], v[40:43]
	v_mfma_f32_16x16x32_bf16 v[32:35], v[116:119], v[176:179], 0
	v_mfma_f32_16x16x32_bf16 v[24:27], v[168:171], v[176:179], 0
	v_mfma_f32_16x16x32_bf16 v[20:23], v[168:171], v[190:193], 0
	v_mfma_f32_16x16x32_bf16 v[28:31], v[116:119], v[190:193], 0
	v_mfma_f32_16x16x32_bf16 v[16:19], v[116:119], v[198:201], 0
	v_mfma_f32_16x16x32_bf16 v[12:15], v[168:171], v[198:201], 0
	v_mfma_f32_16x16x32_bf16 v[2:5], v[168:171], v[214:217], 0
	v_mfma_f32_16x16x32_bf16 v[8:11], v[116:119], v[214:217], 0
	v_mfma_f32_16x16x32_bf16 v[32:35], v[120:123], v[180:183], v[32:35]
	v_mfma_f32_16x16x32_bf16 v[24:27], v[172:175], v[180:183], v[24:27]
	v_mfma_f32_16x16x32_bf16 v[20:23], v[172:175], v[194:197], v[20:23]
	v_mfma_f32_16x16x32_bf16 v[28:31], v[120:123], v[194:197], v[28:31]
	v_mfma_f32_16x16x32_bf16 v[16:19], v[120:123], v[210:213], v[16:19]
	v_mfma_f32_16x16x32_bf16 v[12:15], v[172:175], v[210:213], v[12:15]
	v_mfma_f32_16x16x32_bf16 v[2:5], v[172:175], v[218:221], v[2:5]
	v_mfma_f32_16x16x32_bf16 v[8:11], v[120:123], v[218:221], v[8:11]
	s_barrier
; #define PG8_STAGE(bufoff, gbase, voff) do { _Pragma("unroll") for (int _i = 0; _i < 2; ++_i) \
;         __builtin_amdgcn_global_load_lds((const unsigned*)((const char*)(gbase) + (voff)[_i]), (PG8_LAS unsigned*)(lds + (bufoff) + ldsw + _i * 8192), 16, 0, 0); } while (0)
; #define PG8_LDA(dst, b, h) do { _Pragma("unroll") for (int m = 0; m < 4; ++m) _Pragma("unroll") for (int k = 0; k < 2; ++k) dst[m][k] = *(const PG8_LAS bf16x8*)(lds + PG8_SA(b, h) + aoff + m * 2048 + k * 1024); } while (0)
; #define PG8_LDB(dst, b, h) do { _Pragma("unroll") for (int n = 0; n < 2; ++n) _Pragma("unroll") for (int k = 0; k < 2; ++k) dst[n][k] = *(const PG8_LAS bf16x8*)(lds + PG8_SB(b, h) + boff + n * 2048 + k * 1024); } while (0)
; #define PG8_MMA(ai, bj, At, Bt) do { __builtin_amdgcn_s_setprio(1); _Pragma("unroll") for (int m = 0; m < 4; ++m) _Pragma("unroll") for (int n = 0; n < 2; ++n) _Pragma("unroll") for (int k = 0; k < 2; ++k) \
;         acc[ai][bj][m][n] = mma16<Epi::I8>(Bt[n][k], At[m][k], acc[ai][bj][m][n]); __builtin_amdgcn_s_setprio(0); } while (0)
; #define PG8_WAIT_V(n) asm volatile("s_waitcnt vmcnt(" #n ")" ::: "memory")
; #define PG8_WAIT_L(n) asm volatile("s_waitcnt lgkmcnt(" #n ")" ::: "memory")
; #define PG8_BAR __builtin_amdgcn_s_barrier()
; #define PG8_SCHED __builtin_amdgcn_sched_barrier(0)
; template <class Epi, class Sched, bool ALIGN_EPI = false, bool SP2 = false>
; __device__ __forceinline__ void gemm_phase(PG8_LAS unsigned char* lds, const Gemm g, const Sched& S, const Epi& E) {
;     ...
;         for (int t = 0; t < nt; t += 2) {
;     ...
;             PG8_LDB(B0, 1, 0); PG8_LDB(B1, 1, 1); PG8_SCHED; PG8_LDA(At, 1, 0); PG8_STAGE(PG8_SA(0, 1), a2 + hstep, voffA);
;             PG8_WAIT_V(8); PG8_WAIT_L(0); PG8_BAR; PG8_MMA(0, 0, At, B0); PG8_MMA(0, 1, At, B1); PG8_BAR; PG8_SCHED;
;             PG8_LDA(At, 1, 1); PG8_STAGE(PG8_SB(1, 0), b3, voffB); PG8_STAGE(PG8_SB(1, 1), b3 + hstep, voffB); PG8_STAGE(PG8_SA(1, 0), a3, voffA);
;             PG8_WAIT_V(8); PG8_WAIT_L(0); PG8_BAR; PG8_MMA(1, 0, At, B0); PG8_MMA(1, 1, At, B1); PG8_BAR; PG8_SCHED;
	s_add_i32 s10, 0, 0x18000
	v_add_u32_e32 v0, s10, v188
	s_add_i32 s11, 0, 0x1c000
	ds_read_b128 v[52:55], v0
	ds_read_b128 v[56:59], v0 offset:1024
	ds_read_b128 v[76:79], v0 offset:2048
	ds_read_b128 v[80:83], v0 offset:3072
	v_add_u32_e32 v0, s11, v188
	ds_read_b128 v[116:119], v0
	ds_read_b128 v[120:123], v0 offset:1024
	ds_read_b128 v[168:171], v0 offset:2048
	ds_read_b128 v[172:175], v0 offset:3072
	s_add_u32 s8, vcc_lo, 0x80000
	s_addc_u32 s9, vcc_hi, 0
	s_mov_b32 m0, s13
	ds_read_b128 v[176:179], v189 offset:32768
	ds_read_b128 v[180:183], v189 offset:33792
	ds_read_b128 v[190:193], v189 offset:34816
	ds_read_b128 v[194:197], v189 offset:35840
	ds_read_b128 v[198:201], v189 offset:36864
	ds_read_b128 v[210:213], v189 offset:37888
	ds_read_b128 v[214:217], v189 offset:38912
	ds_read_b128 v[218:221], v189 offset:39936
	global_load_lds_dwordx4 v156, s[8:9]
	s_mov_b32 m0, s66
	s_nop 0
	global_load_lds_dwordx4 v160, s[8:9]
	s_waitcnt vmcnt(8)
	s_waitcnt lgkmcnt(0)
	s_barrier
	s_waitcnt lgkmcnt(0)
	v_mfma_f32_16x16x32_bf16 v[152:155], v[52:55], v[176:179], v[152:155]
	v_mfma_f32_16x16x32_bf16 v[144:147], v[76:79], v[176:179], v[144:147]
	v_mfma_f32_16x16x32_bf16 v[140:143], v[76:79], v[190:193], v[140:143]
	v_mfma_f32_16x16x32_bf16 v[148:151], v[52:55], v[190:193], v[148:151]
	v_mfma_f32_16x16x32_bf16 v[136:139], v[52:55], v[198:201], v[136:139]
	v_mfma_f32_16x16x32_bf16 v[132:135], v[76:79], v[198:201], v[132:135]
	v_mfma_f32_16x16x32_bf16 v[124:127], v[76:79], v[214:217], v[124:127]
	v_mfma_f32_16x16x32_bf16 v[128:131], v[52:55], v[214:217], v[128:131]
	v_mfma_f32_16x16x32_bf16 v[152:155], v[56:59], v[180:183], v[152:155]
	v_mfma_f32_16x16x32_bf16 v[144:147], v[80:83], v[180:183], v[144:147]
	v_mfma_f32_16x16x32_bf16 v[140:143], v[80:83], v[194:197], v[140:143]
	v_mfma_f32_16x16x32_bf16 v[148:151], v[56:59], v[194:197], v[148:151]
	v_mfma_f32_16x16x32_bf16 v[136:139], v[56:59], v[210:213], v[136:139]
	v_mfma_f32_16x16x32_bf16 v[132:135], v[80:83], v[210:213], v[132:135]
	v_mfma_f32_16x16x32_bf16 v[124:127], v[80:83], v[218:221], v[124:127]
	v_mfma_f32_16x16x32_bf16 v[128:131], v[56:59], v[218:221], v[128:131]
	v_mfma_f32_16x16x32_bf16 v[112:115], v[116:119], v[176:179], v[112:115]
	v_mfma_f32_16x16x32_bf16 v[104:107], v[168:171], v[176:179], v[104:107]
	v_mfma_f32_16x16x32_bf16 v[100:103], v[168:171], v[190:193], v[100:103]
	v_mfma_f32_16x16x32_bf16 v[108:111], v[116:119], v[190:193], v[108:111]
	v_mfma_f32_16x16x32_bf16 v[96:99], v[116:119], v[198:201], v[96:99]
	v_mfma_f32_16x16x32_bf16 v[92:95], v[168:171], v[198:201], v[92:95]
	v_mfma_f32_16x16x32_bf16 v[84:87], v[168:171], v[214:217], v[84:87]
	v_mfma_f32_16x16x32_bf16 v[88:91], v[116:119], v[214:217], v[88:91]
	v_mfma_f32_16x16x32_bf16 v[112:115], v[120:123], v[180:183], v[112:115]
	v_mfma_f32_16x16x32_bf16 v[104:107], v[172:175], v[180:183], v[104:107]
	v_mfma_f32_16x16x32_bf16 v[100:103], v[172:175], v[194:197], v[100:103]
	v_mfma_f32_16x16x32_bf16 v[108:111], v[120:123], v[194:197], v[108:111]
	v_mfma_f32_16x16x32_bf16 v[96:99], v[120:123], v[210:213], v[96:99]
	v_mfma_f32_16x16x32_bf16 v[92:95], v[172:175], v[210:213], v[92:95]
	v_mfma_f32_16x16x32_bf16 v[84:87], v[172:175], v[218:221], v[84:87]
	v_mfma_f32_16x16x32_bf16 v[88:91], v[120:123], v[218:221], v[88:91]
	s_barrier
	s_add_i32 s8, s10, s80
	s_add_u32 s98, s70, 0x80
	s_addc_u32 s99, s71, 0
	s_add_u32 s100, vcc_lo, 0x80
	s_addc_u32 s101, vcc_hi, 0
	s_mov_b32 m0, s8
	ds_read_b128 v[176:179], v189 offset:49152
	ds_read_b128 v[180:183], v189 offset:50176
	ds_read_b128 v[190:193], v189 offset:51200
	ds_read_b128 v[194:197], v189 offset:52224
	ds_read_b128 v[198:201], v189 offset:53248
	ds_read_b128 v[210:213], v189 offset:54272
	ds_read_b128 v[214:217], v189 offset:55296
	ds_read_b128 v[218:221], v189 offset:56320
	global_load_lds_dwordx4 v158, s[98:99]
	s_add_i32 m0, s8, 0x2000
	s_add_u32 s8, s70, 0x80080
	s_addc_u32 s9, s71, 0
	s_add_i32 s10, s11, s80
	global_load_lds_dwordx4 v162, s[98:99]
	s_mov_b32 m0, s10
	s_nop 0
	global_load_lds_dwordx4 v158, s[8:9]
	s_add_i32 m0, s10, 0x2000
	s_nop 0
	global_load_lds_dwordx4 v162, s[8:9]
	s_mov_b32 m0, s67
	s_nop 0
	global_load_lds_dwordx4 v156, s[100:101]
	s_mov_b32 m0, s81
	s_nop 0
	global_load_lds_dwordx4 v160, s[100:101]
	s_waitcnt vmcnt(8)
	s_waitcnt lgkmcnt(0)
	s_barrier
	s_waitcnt lgkmcnt(0)
	v_mfma_f32_16x16x32_bf16 v[72:75], v[52:55], v[176:179], v[72:75]
	v_mfma_f32_16x16x32_bf16 v[64:67], v[76:79], v[176:179], v[64:67]
	v_mfma_f32_16x16x32_bf16 v[60:63], v[76:79], v[190:193], v[60:63]
	v_mfma_f32_16x16x32_bf16 v[68:71], v[52:55], v[190:193], v[68:71]
	v_mfma_f32_16x16x32_bf16 v[48:51], v[52:55], v[198:201], v[48:51]
	v_mfma_f32_16x16x32_bf16 v[44:47], v[76:79], v[198:201], v[44:47]
	v_mfma_f32_16x16x32_bf16 v[36:39], v[76:79], v[214:217], v[36:39]
	v_mfma_f32_16x16x32_bf16 v[40:43], v[52:55], v[214:217], v[40:43]
	v_mfma_f32_16x16x32_bf16 v[72:75], v[56:59], v[180:183], v[72:75]
	v_mfma_f32_16x16x32_bf16 v[64:67], v[80:83], v[180:183], v[64:67]
	v_mfma_f32_16x16x32_bf16 v[60:63], v[80:83], v[194:197], v[60:63]
	v_mfma_f32_16x16x32_bf16 v[68:71], v[56:59], v[194:197], v[68:71]
	v_mfma_f32_16x16x32_bf16 v[48:51], v[56:59], v[210:213], v[48:51]
	v_mfma_f32_16x16x32_bf16 v[44:47], v[80:83], v[210:213], v[44:47]
	v_mfma_f32_16x16x32_bf16 v[36:39], v[80:83], v[218:221], v[36:39]
	v_mfma_f32_16x16x32_bf16 v[40:43], v[56:59], v[218:221], v[40:43]
	v_mfma_f32_16x16x32_bf16 v[32:35], v[116:119], v[176:179], v[32:35]
	v_mfma_f32_16x16x32_bf16 v[24:27], v[168:171], v[176:179], v[24:27]
	v_mfma_f32_16x16x32_bf16 v[20:23], v[168:171], v[190:193], v[20:23]
	v_mfma_f32_16x16x32_bf16 v[28:31], v[116:119], v[190:193], v[28:31]
	v_mfma_f32_16x16x32_bf16 v[16:19], v[116:119], v[198:201], v[16:19]
	v_mfma_f32_16x16x32_bf16 v[12:15], v[168:171], v[198:201], v[12:15]
	v_mfma_f32_16x16x32_bf16 v[2:5], v[168:171], v[214:217], v[2:5]
	v_mfma_f32_16x16x32_bf16 v[6:9], v[116:119], v[214:217], v[8:11]
	v_mfma_f32_16x16x32_bf16 v[32:35], v[120:123], v[180:183], v[32:35]
	v_mfma_f32_16x16x32_bf16 v[24:27], v[172:175], v[180:183], v[24:27]
	v_mfma_f32_16x16x32_bf16 v[20:23], v[172:175], v[194:197], v[20:23]
	v_mfma_f32_16x16x32_bf16 v[28:31], v[120:123], v[194:197], v[28:31]
	v_mfma_f32_16x16x32_bf16 v[16:19], v[120:123], v[210:213], v[16:19]
	v_mfma_f32_16x16x32_bf16 v[12:15], v[172:175], v[210:213], v[12:15]
	v_mfma_f32_16x16x32_bf16 v[8:11], v[120:123], v[218:221], v[6:9]
	v_mfma_f32_16x16x32_bf16 v[4:7], v[172:175], v[218:221], v[2:5]
	s_barrier
	s_add_i32 s4, s4, 2
	s_add_u32 s97, s97, 0x100
	s_addc_u32 s96, s96, 0
	s_cmp_gt_u32 s4, 29
	s_mov_b64 s[8:9], s[68:69]
	s_cbranch_scc0 .LBB0_327
	s_branch .Lpeelx327
; #define PG8_STAGE(bufoff, gbase, voff) do { _Pragma("unroll") for (int _i = 0; _i < 2; ++_i) \
;         __builtin_amdgcn_global_load_lds((const unsigned*)((const char*)(gbase) + (voff)[_i]), (PG8_LAS unsigned*)(lds + (bufoff) + ldsw + _i * 8192), 16, 0, 0); } while (0)
; #define PG8_LDA(dst, b, h) do { _Pragma("unroll") for (int m = 0; m < 4; ++m) _Pragma("unroll") for (int k = 0; k < 2; ++k) dst[m][k] = *(const PG8_LAS bf16x8*)(lds + PG8_SA(b, h) + aoff + m * 2048 + k * 1024); } while (0)
; #define PG8_LDB(dst, b, h) do { _Pragma("unroll") for (int n = 0; n < 2; ++n) _Pragma("unroll") for (int k = 0; k < 2; ++k) dst[n][k] = *(const PG8_LAS bf16x8*)(lds + PG8_SB(b, h) + boff + n * 2048 + k * 1024); } while (0)
; #define PG8_MMA(ai, bj, At, Bt) do { __builtin_amdgcn_s_setprio(1); _Pragma("unroll") for (int m = 0; m < 4; ++m) _Pragma("unroll") for (int n = 0; n < 2; ++n) _Pragma("unroll") for (int k = 0; k < 2; ++k) \
;         acc[ai][bj][m][n] = mma16<Epi::I8>(Bt[n][k], At[m][k], acc[ai][bj][m][n]); __builtin_amdgcn_s_setprio(0); } while (0)
; #define PG8_WAIT_V(n) asm volatile("s_waitcnt vmcnt(" #n ")" ::: "memory")
; #define PG8_WAIT_L(n) asm volatile("s_waitcnt lgkmcnt(" #n ")" ::: "memory")
; #define PG8_BAR __builtin_amdgcn_s_barrier()
; #define PG8_SCHED __builtin_amdgcn_sched_barrier(0)
; template <class Epi, class Sched, bool ALIGN_EPI = false, bool SP2 = false>
; __device__ __forceinline__ void gemm_phase(PG8_LAS unsigned char* lds, const Gemm g, const Sched& S, const Epi& E) {
;     ...
;             const char* a1 = cA + (size_t)(t + 1) * kstep;
;             const char* a2 = last ? nA : cA + (size_t)(t + 2) * kstep; const char* b2 = last ? nB : cB + (size_t)(t + 2) * kstep;
;             const char* a3 = a2 + kstep; const char* b3 = b2 + kstep;
;             if (last && has_next) S.a_ready(nxt);
;             if constexpr (SP2) {
;             PG8_LDB(B0, 0, 0); PG8_LDB(B1, 0, 1); PG8_SCHED; PG8_LDA(At, 0, 0); PG8_STAGE(PG8_SA(1, 1), a1 + hstep, voffA);
;             PG8_WAIT_V(8); PG8_WAIT_L(0); PG8_BAR; PG8_MMA(0, 0, At, B0); PG8_MMA(0, 1, At, B1); PG8_BAR; PG8_SCHED;
;             PG8_LDA(At, 0, 1); PG8_STAGE(PG8_SB(0, 0), b2, voffB); PG8_STAGE(PG8_SB(0, 1), b2 + hstep, voffB); PG8_STAGE(PG8_SA(0, 0), a2, voffA);
;             PG8_WAIT_V(8); PG8_WAIT_L(0); PG8_BAR; PG8_MMA(1, 0, At, B0); PG8_MMA(1, 1, At, B1); PG8_BAR; PG8_SCHED;
.LBB0_327:
	s_add_u32 s68, s8, 0x100
	s_addc_u32 s69, s9, 0
	s_add_i32 s84, 0, 0x10000
	s_cmp_eq_u32 s4, 28
	s_cselect_b32 vcc_hi, s1, s69
	s_cselect_b32 vcc_lo, s5, s68
	v_add_u32_e32 v0, s84, v188
	s_cselect_b32 s71, s7, s96
	s_cselect_b32 s70, s85, s97
	s_add_i32 s10, 0, 0x14000
	ds_read_b128 v[52:55], v0
	ds_read_b128 v[56:59], v0 offset:1024
	ds_read_b128 v[76:79], v0 offset:2048
	ds_read_b128 v[80:83], v0 offset:3072
	v_add_u32_e32 v0, s10, v188
	ds_read_b128 v[116:119], v0
	ds_read_b128 v[120:123], v0 offset:1024
	ds_read_b128 v[168:171], v0 offset:2048
	ds_read_b128 v[172:175], v0 offset:3072
	s_add_i32 m0, s58, 0xc000
	ds_read_b128 v[176:179], v189
	ds_read_b128 v[180:183], v189 offset:1024
	ds_read_b128 v[190:193], v189 offset:2048
	ds_read_b128 v[194:197], v189 offset:3072
	ds_read_b128 v[198:201], v189 offset:4096
	ds_read_b128 v[210:213], v189 offset:5120
	ds_read_b128 v[214:217], v189 offset:6144
	ds_read_b128 v[218:221], v189 offset:7168
	global_load_lds_dwordx4 v164, s[8:9]
	s_add_i32 m0, s58, 0xe000
	s_nop 0
	global_load_lds_dwordx4 v166, s[8:9]
	s_waitcnt vmcnt(8)
	s_waitcnt lgkmcnt(0)
	s_barrier
	s_waitcnt lgkmcnt(0)
	v_mfma_f32_16x16x32_bf16 v[152:155], v[52:55], v[176:179], v[152:155]
	v_mfma_f32_16x16x32_bf16 v[144:147], v[76:79], v[176:179], v[144:147]
	v_mfma_f32_16x16x32_bf16 v[140:143], v[76:79], v[190:193], v[140:143]
	v_mfma_f32_16x16x32_bf16 v[148:151], v[52:55], v[190:193], v[148:151]
	v_mfma_f32_16x16x32_bf16 v[136:139], v[52:55], v[198:201], v[136:139]
	v_mfma_f32_16x16x32_bf16 v[132:135], v[76:79], v[198:201], v[132:135]
	v_mfma_f32_16x16x32_bf16 v[124:127], v[76:79], v[214:217], v[124:127]
	v_mfma_f32_16x16x32_bf16 v[128:131], v[52:55], v[214:217], v[128:131]
	v_mfma_f32_16x16x32_bf16 v[152:155], v[56:59], v[180:183], v[152:155]
	v_mfma_f32_16x16x32_bf16 v[144:147], v[80:83], v[180:183], v[144:147]
	v_mfma_f32_16x16x32_bf16 v[140:143], v[80:83], v[194:197], v[140:143]
	v_mfma_f32_16x16x32_bf16 v[148:151], v[56:59], v[194:197], v[148:151]
	v_mfma_f32_16x16x32_bf16 v[136:139], v[56:59], v[210:213], v[136:139]
	v_mfma_f32_16x16x32_bf16 v[132:135], v[80:83], v[210:213], v[132:135]
	v_mfma_f32_16x16x32_bf16 v[124:127], v[80:83], v[218:221], v[124:127]
	v_mfma_f32_16x16x32_bf16 v[128:131], v[56:59], v[218:221], v[128:131]
	v_mfma_f32_16x16x32_bf16 v[112:115], v[116:119], v[176:179], v[112:115]
	v_mfma_f32_16x16x32_bf16 v[104:107], v[168:171], v[176:179], v[104:107]
	v_mfma_f32_16x16x32_bf16 v[100:103], v[168:171], v[190:193], v[100:103]
	v_mfma_f32_16x16x32_bf16 v[108:111], v[116:119], v[190:193], v[108:111]
	v_mfma_f32_16x16x32_bf16 v[96:99], v[116:119], v[198:201], v[96:99]
	v_mfma_f32_16x16x32_bf16 v[92:95], v[168:171], v[198:201], v[92:95]
	v_mfma_f32_16x16x32_bf16 v[84:87], v[168:171], v[214:217], v[84:87]
	v_mfma_f32_16x16x32_bf16 v[88:91], v[116:119], v[214:217], v[88:91]
	v_mfma_f32_16x16x32_bf16 v[112:115], v[120:123], v[180:183], v[112:115]
	v_mfma_f32_16x16x32_bf16 v[104:107], v[172:175], v[180:183], v[104:107]
	v_mfma_f32_16x16x32_bf16 v[100:103], v[172:175], v[194:197], v[100:103]
	v_mfma_f32_16x16x32_bf16 v[108:111], v[120:123], v[194:197], v[108:111]
	v_mfma_f32_16x16x32_bf16 v[96:99], v[120:123], v[210:213], v[96:99]
	v_mfma_f32_16x16x32_bf16 v[92:95], v[172:175], v[210:213], v[92:95]
	v_mfma_f32_16x16x32_bf16 v[84:87], v[172:175], v[218:221], v[84:87]
	v_mfma_f32_16x16x32_bf16 v[88:91], v[120:123], v[218:221], v[88:91]
	s_barrier
	s_add_i32 s8, s84, s80
	s_mov_b32 m0, s8
	ds_read_b128 v[176:179], v189 offset:16384
	ds_read_b128 v[180:183], v189 offset:17408
	ds_read_b128 v[190:193], v189 offset:18432
	ds_read_b128 v[194:197], v189 offset:19456
	ds_read_b128 v[198:201], v189 offset:20480
	ds_read_b128 v[210:213], v189 offset:21504
	ds_read_b128 v[214:217], v189 offset:22528
	ds_read_b128 v[218:221], v189 offset:23552
	global_load_lds_dwordx4 v158, s[70:71]
	s_add_i32 m0, s8, 0x2000
	s_add_u32 s8, s70, 0x80000
	s_addc_u32 s9, s71, 0
	s_add_i32 s10, s10, s80
	global_load_lds_dwordx4 v162, s[70:71]
	s_mov_b32 m0, s10
	s_nop 0
	global_load_lds_dwordx4 v158, s[8:9]
	s_add_i32 m0, s10, 0x2000
	s_nop 0
	global_load_lds_dwordx4 v162, s[8:9]
	s_mov_b32 m0, s58
	s_nop 0
	global_load_lds_dwordx4 v156, vcc
	s_mov_b32 m0, s12
	s_nop 0
	global_load_lds_dwordx4 v160, vcc
	s_waitcnt vmcnt(8)
	s_waitcnt lgkmcnt(0)
	s_barrier
	s_waitcnt lgkmcnt(0)
	v_mfma_f32_16x16x32_bf16 v[72:75], v[52:55], v[176:179], v[72:75]
	v_mfma_f32_16x16x32_bf16 v[64:67], v[76:79], v[176:179], v[64:67]
	v_mfma_f32_16x16x32_bf16 v[60:63], v[76:79], v[190:193], v[60:63]
	v_mfma_f32_16x16x32_bf16 v[68:71], v[52:55], v[190:193], v[68:71]
	v_mfma_f32_16x16x32_bf16 v[48:51], v[52:55], v[198:201], v[48:51]
	v_mfma_f32_16x16x32_bf16 v[44:47], v[76:79], v[198:201], v[44:47]
	v_mfma_f32_16x16x32_bf16 v[36:39], v[76:79], v[214:217], v[36:39]
	v_mfma_f32_16x16x32_bf16 v[40:43], v[52:55], v[214:217], v[40:43]
	v_mfma_f32_16x16x32_bf16 v[72:75], v[56:59], v[180:183], v[72:75]
	v_mfma_f32_16x16x32_bf16 v[64:67], v[80:83], v[180:183], v[64:67]
	v_mfma_f32_16x16x32_bf16 v[60:63], v[80:83], v[194:197], v[60:63]
	v_mfma_f32_16x16x32_bf16 v[68:71], v[56:59], v[194:197], v[68:71]
	v_mfma_f32_16x16x32_bf16 v[48:51], v[56:59], v[210:213], v[48:51]
	v_mfma_f32_16x16x32_bf16 v[44:47], v[80:83], v[210:213], v[44:47]
	v_mfma_f32_16x16x32_bf16 v[36:39], v[80:83], v[218:221], v[36:39]
	v_mfma_f32_16x16x32_bf16 v[40:43], v[56:59], v[218:221], v[40:43]
	v_mfma_f32_16x16x32_bf16 v[32:35], v[116:119], v[176:179], v[32:35]
	v_mfma_f32_16x16x32_bf16 v[24:27], v[168:171], v[176:179], v[24:27]
	v_mfma_f32_16x16x32_bf16 v[20:23], v[168:171], v[190:193], v[20:23]
	v_mfma_f32_16x16x32_bf16 v[28:31], v[116:119], v[190:193], v[28:31]
	v_mfma_f32_16x16x32_bf16 v[16:19], v[116:119], v[198:201], v[16:19]
	v_mfma_f32_16x16x32_bf16 v[12:15], v[168:171], v[198:201], v[12:15]
	v_mfma_f32_16x16x32_bf16 v[2:5], v[168:171], v[214:217], v[4:7]
	v_mfma_f32_16x16x32_bf16 v[8:11], v[116:119], v[214:217], v[8:11]
	v_mfma_f32_16x16x32_bf16 v[32:35], v[120:123], v[180:183], v[32:35]
	v_mfma_f32_16x16x32_bf16 v[24:27], v[172:175], v[180:183], v[24:27]
	v_mfma_f32_16x16x32_bf16 v[20:23], v[172:175], v[194:197], v[20:23]
	v_mfma_f32_16x16x32_bf16 v[28:31], v[120:123], v[194:197], v[28:31]
	v_mfma_f32_16x16x32_bf16 v[16:19], v[120:123], v[210:213], v[16:19]
	v_mfma_f32_16x16x32_bf16 v[12:15], v[172:175], v[210:213], v[12:15]
	v_mfma_f32_16x16x32_bf16 v[2:5], v[172:175], v[218:221], v[2:5]
	v_mfma_f32_16x16x32_bf16 v[8:11], v[120:123], v[218:221], v[8:11]
	s_barrier
; #define PG8_STAGE(bufoff, gbase, voff) do { _Pragma("unroll") for (int _i = 0; _i < 2; ++_i) \
;         __builtin_amdgcn_global_load_lds((const unsigned*)((const char*)(gbase) + (voff)[_i]), (PG8_LAS unsigned*)(lds + (bufoff) + ldsw + _i * 8192), 16, 0, 0); } while (0)
; #define PG8_LDA(dst, b, h) do { _Pragma("unroll") for (int m = 0; m < 4; ++m) _Pragma("unroll") for (int k = 0; k < 2; ++k) dst[m][k] = *(const PG8_LAS bf16x8*)(lds + PG8_SA(b, h) + aoff + m * 2048 + k * 1024); } while (0)
; #define PG8_LDB(dst, b, h) do { _Pragma("unroll") for (int n = 0; n < 2; ++n) _Pragma("unroll") for (int k = 0; k < 2; ++k) dst[n][k] = *(const PG8_LAS bf16x8*)(lds + PG8_SB(b, h) + boff + n * 2048 + k * 1024); } while (0)
; #define PG8_MMA(ai, bj, At, Bt) do { __builtin_amdgcn_s_setprio(1); _Pragma("unroll") for (int m = 0; m < 4; ++m) _Pragma("unroll") for (int n = 0; n < 2; ++n) _Pragma("unroll") for (int k = 0; k < 2; ++k) \
;         acc[ai][bj][m][n] = mma16<Epi::I8>(Bt[n][k], At[m][k], acc[ai][bj][m][n]); __builtin_amdgcn_s_setprio(0); } while (0)
; #define PG8_WAIT_V(n) asm volatile("s_waitcnt vmcnt(" #n ")" ::: "memory")
; #define PG8_WAIT_L(n) asm volatile("s_waitcnt lgkmcnt(" #n ")" ::: "memory")
; #define PG8_BAR __builtin_amdgcn_s_barrier()
; #define PG8_SCHED __builtin_amdgcn_sched_barrier(0)
; template <class Epi, class Sched, bool ALIGN_EPI = false, bool SP2 = false>
; __device__ __forceinline__ void gemm_phase(PG8_LAS unsigned char* lds, const Gemm g, const Sched& S, const Epi& E) {
;     ...
;             PG8_LDB(B0, 1, 0); PG8_LDB(B1, 1, 1); PG8_SCHED; PG8_LDA(At, 1, 0); PG8_STAGE(PG8_SA(0, 1), a2 + hstep, voffA);
;             PG8_WAIT_V(8); PG8_WAIT_L(0); PG8_BAR; PG8_MMA(0, 0, At, B0); PG8_MMA(0, 1, At, B1); PG8_BAR; PG8_SCHED;
;             PG8_LDA(At, 1, 1); PG8_STAGE(PG8_SB(1, 0), b3, voffB); PG8_STAGE(PG8_SB(1, 1), b3 + hstep, voffB); PG8_STAGE(PG8_SA(1, 0), a3, voffA);
;             PG8_WAIT_V(8); PG8_WAIT_L(0); PG8_BAR; PG8_MMA(1, 0, At, B0); PG8_MMA(1, 1, At, B1); PG8_BAR; PG8_SCHED;
	s_add_i32 s10, 0, 0x18000
	v_add_u32_e32 v0, s10, v188
	s_add_i32 s11, 0, 0x1c000
	ds_read_b128 v[52:55], v0
	ds_read_b128 v[56:59], v0 offset:1024
	ds_read_b128 v[76:79], v0 offset:2048
	ds_read_b128 v[80:83], v0 offset:3072
	v_add_u32_e32 v0, s11, v188
	ds_read_b128 v[116:119], v0
	ds_read_b128 v[120:123], v0 offset:1024
	ds_read_b128 v[168:171], v0 offset:2048
	ds_read_b128 v[172:175], v0 offset:3072
	s_add_u32 s8, vcc_lo, 0x80000
	s_addc_u32 s9, vcc_hi, 0
	s_mov_b32 m0, s13
	ds_read_b128 v[176:179], v189 offset:32768
	ds_read_b128 v[180:183], v189 offset:33792
	ds_read_b128 v[190:193], v189 offset:34816
	ds_read_b128 v[194:197], v189 offset:35840
	ds_read_b128 v[198:201], v189 offset:36864
	ds_read_b128 v[210:213], v189 offset:37888
	ds_read_b128 v[214:217], v189 offset:38912
	ds_read_b128 v[218:221], v189 offset:39936
	global_load_lds_dwordx4 v156, s[8:9]
	s_mov_b32 m0, s66
	s_nop 0
	global_load_lds_dwordx4 v160, s[8:9]
	s_waitcnt vmcnt(8)
	s_waitcnt lgkmcnt(0)
	s_barrier
	s_waitcnt lgkmcnt(0)
	v_mfma_f32_16x16x32_bf16 v[152:155], v[52:55], v[176:179], v[152:155]
	v_mfma_f32_16x16x32_bf16 v[144:147], v[76:79], v[176:179], v[144:147]
	v_mfma_f32_16x16x32_bf16 v[140:143], v[76:79], v[190:193], v[140:143]
	v_mfma_f32_16x16x32_bf16 v[148:151], v[52:55], v[190:193], v[148:151]
	v_mfma_f32_16x16x32_bf16 v[136:139], v[52:55], v[198:201], v[136:139]
	v_mfma_f32_16x16x32_bf16 v[132:135], v[76:79], v[198:201], v[132:135]
	v_mfma_f32_16x16x32_bf16 v[124:127], v[76:79], v[214:217], v[124:127]
	v_mfma_f32_16x16x32_bf16 v[128:131], v[52:55], v[214:217], v[128:131]
	v_mfma_f32_16x16x32_bf16 v[152:155], v[56:59], v[180:183], v[152:155]
	v_mfma_f32_16x16x32_bf16 v[144:147], v[80:83], v[180:183], v[144:147]
	v_mfma_f32_16x16x32_bf16 v[140:143], v[80:83], v[194:197], v[140:143]
	v_mfma_f32_16x16x32_bf16 v[148:151], v[56:59], v[194:197], v[148:151]
	v_mfma_f32_16x16x32_bf16 v[136:139], v[56:59], v[210:213], v[136:139]
	v_mfma_f32_16x16x32_bf16 v[132:135], v[80:83], v[210:213], v[132:135]
	v_mfma_f32_16x16x32_bf16 v[124:127], v[80:83], v[218:221], v[124:127]
	v_mfma_f32_16x16x32_bf16 v[128:131], v[56:59], v[218:221], v[128:131]
	v_mfma_f32_16x16x32_bf16 v[112:115], v[116:119], v[176:179], v[112:115]
	v_mfma_f32_16x16x32_bf16 v[104:107], v[168:171], v[176:179], v[104:107]
	v_mfma_f32_16x16x32_bf16 v[100:103], v[168:171], v[190:193], v[100:103]
	v_mfma_f32_16x16x32_bf16 v[108:111], v[116:119], v[190:193], v[108:111]
	v_mfma_f32_16x16x32_bf16 v[96:99], v[116:119], v[198:201], v[96:99]
	v_mfma_f32_16x16x32_bf16 v[92:95], v[168:171], v[198:201], v[92:95]
	v_mfma_f32_16x16x32_bf16 v[84:87], v[168:171], v[214:217], v[84:87]
	v_mfma_f32_16x16x32_bf16 v[88:91], v[116:119], v[214:217], v[88:91]
	v_mfma_f32_16x16x32_bf16 v[112:115], v[120:123], v[180:183], v[112:115]
	v_mfma_f32_16x16x32_bf16 v[104:107], v[172:175], v[180:183], v[104:107]
	v_mfma_f32_16x16x32_bf16 v[100:103], v[172:175], v[194:197], v[100:103]
	v_mfma_f32_16x16x32_bf16 v[108:111], v[120:123], v[194:197], v[108:111]
	v_mfma_f32_16x16x32_bf16 v[96:99], v[120:123], v[210:213], v[96:99]
	v_mfma_f32_16x16x32_bf16 v[92:95], v[172:175], v[210:213], v[92:95]
	v_mfma_f32_16x16x32_bf16 v[84:87], v[172:175], v[218:221], v[84:87]
	v_mfma_f32_16x16x32_bf16 v[88:91], v[120:123], v[218:221], v[88:91]
	s_barrier
	s_add_i32 s8, s10, s80
	s_add_u32 s98, s70, 0x80
	s_addc_u32 s99, s71, 0
	s_add_u32 s100, vcc_lo, 0x80
	s_addc_u32 s101, vcc_hi, 0
	s_mov_b32 m0, s8
	ds_read_b128 v[176:179], v189 offset:49152
	ds_read_b128 v[180:183], v189 offset:50176
	ds_read_b128 v[190:193], v189 offset:51200
	ds_read_b128 v[194:197], v189 offset:52224
	ds_read_b128 v[198:201], v189 offset:53248
	ds_read_b128 v[210:213], v189 offset:54272
	ds_read_b128 v[214:217], v189 offset:55296
	ds_read_b128 v[218:221], v189 offset:56320
	global_load_lds_dwordx4 v158, s[98:99]
	s_add_i32 m0, s8, 0x2000
	s_add_u32 s8, s70, 0x80080
	s_addc_u32 s9, s71, 0
	s_add_i32 s10, s11, s80
	global_load_lds_dwordx4 v162, s[98:99]
	s_mov_b32 m0, s10
	s_nop 0
	global_load_lds_dwordx4 v158, s[8:9]
	s_add_i32 m0, s10, 0x2000
	s_nop 0
	global_load_lds_dwordx4 v162, s[8:9]
	s_mov_b32 m0, s67
	s_nop 0
	global_load_lds_dwordx4 v156, s[100:101]
	s_mov_b32 m0, s81
	s_nop 0
	global_load_lds_dwordx4 v160, s[100:101]
	s_waitcnt vmcnt(8)
	s_waitcnt lgkmcnt(0)
	s_barrier
	s_waitcnt lgkmcnt(0)
	v_mfma_f32_16x16x32_bf16 v[72:75], v[52:55], v[176:179], v[72:75]
	v_mfma_f32_16x16x32_bf16 v[64:67], v[76:79], v[176:179], v[64:67]
	v_mfma_f32_16x16x32_bf16 v[60:63], v[76:79], v[190:193], v[60:63]
	v_mfma_f32_16x16x32_bf16 v[68:71], v[52:55], v[190:193], v[68:71]
	v_mfma_f32_16x16x32_bf16 v[48:51], v[52:55], v[198:201], v[48:51]
	v_mfma_f32_16x16x32_bf16 v[44:47], v[76:79], v[198:201], v[44:47]
	v_mfma_f32_16x16x32_bf16 v[36:39], v[76:79], v[214:217], v[36:39]
	v_mfma_f32_16x16x32_bf16 v[40:43], v[52:55], v[214:217], v[40:43]
	v_mfma_f32_16x16x32_bf16 v[72:75], v[56:59], v[180:183], v[72:75]
	v_mfma_f32_16x16x32_bf16 v[64:67], v[80:83], v[180:183], v[64:67]
	v_mfma_f32_16x16x32_bf16 v[60:63], v[80:83], v[194:197], v[60:63]
	v_mfma_f32_16x16x32_bf16 v[68:71], v[56:59], v[194:197], v[68:71]
	v_mfma_f32_16x16x32_bf16 v[48:51], v[56:59], v[210:213], v[48:51]
	v_mfma_f32_16x16x32_bf16 v[44:47], v[80:83], v[210:213], v[44:47]
	v_mfma_f32_16x16x32_bf16 v[36:39], v[80:83], v[218:221], v[36:39]
	v_mfma_f32_16x16x32_bf16 v[40:43], v[56:59], v[218:221], v[40:43]
	v_mfma_f32_16x16x32_bf16 v[32:35], v[116:119], v[176:179], v[32:35]
	v_mfma_f32_16x16x32_bf16 v[24:27], v[168:171], v[176:179], v[24:27]
	v_mfma_f32_16x16x32_bf16 v[20:23], v[168:171], v[190:193], v[20:23]
	v_mfma_f32_16x16x32_bf16 v[28:31], v[116:119], v[190:193], v[28:31]
	v_mfma_f32_16x16x32_bf16 v[16:19], v[116:119], v[198:201], v[16:19]
	v_mfma_f32_16x16x32_bf16 v[12:15], v[168:171], v[198:201], v[12:15]
	v_mfma_f32_16x16x32_bf16 v[2:5], v[168:171], v[214:217], v[2:5]
	v_mfma_f32_16x16x32_bf16 v[6:9], v[116:119], v[214:217], v[8:11]
	v_mfma_f32_16x16x32_bf16 v[32:35], v[120:123], v[180:183], v[32:35]
	v_mfma_f32_16x16x32_bf16 v[24:27], v[172:175], v[180:183], v[24:27]
	v_mfma_f32_16x16x32_bf16 v[20:23], v[172:175], v[194:197], v[20:23]
	v_mfma_f32_16x16x32_bf16 v[28:31], v[120:123], v[194:197], v[28:31]
	v_mfma_f32_16x16x32_bf16 v[16:19], v[120:123], v[210:213], v[16:19]
	v_mfma_f32_16x16x32_bf16 v[12:15], v[172:175], v[210:213], v[12:15]
	v_mfma_f32_16x16x32_bf16 v[8:11], v[120:123], v[218:221], v[6:9]
	v_mfma_f32_16x16x32_bf16 v[4:7], v[172:175], v[218:221], v[2:5]
	s_barrier
	s_add_i32 s4, s4, 2
	s_add_u32 s97, s97, 0x100
	s_addc_u32 s96, s96, 0
	s_cmp_gt_u32 s4, 29
	s_mov_b64 s[8:9], s[68:69]
	s_cbranch_scc0 .LBB0_327

; #define PG8_STAGE(bufoff, gbase, voff) do { _Pragma("unroll") for (int _i = 0; _i < 2; ++_i) \
;         __builtin_amdgcn_global_load_lds((const unsigned*)((const char*)(gbase) + (voff)[_i]), (PG8_LAS unsigned*)(lds + (bufoff) + ldsw + _i * 8192), 16, 0, 0); } while (0)
; #define PG8_LDA(dst, b, h) do { _Pragma("unroll") for (int m = 0; m < 4; ++m) _Pragma("unroll") for (int k = 0; k < 2; ++k) dst[m][k] = *(const PG8_LAS bf16x8*)(lds + PG8_SA(b, h) + aoff + m * 2048 + k * 1024); } while (0)
; #define PG8_LDB(dst, b, h) do { _Pragma("unroll") for (int n = 0; n < 2; ++n) _Pragma("unroll") for (int k = 0; k < 2; ++k) dst[n][k] = *(const PG8_LAS bf16x8*)(lds + PG8_SB(b, h) + boff + n * 2048 + k * 1024); } while (0)
; #define PG8_MMA(ai, bj, At, Bt) do { __builtin_amdgcn_s_setprio(1); _Pragma("unroll") for (int m = 0; m < 4; ++m) _Pragma("unroll") for (int n = 0; n < 2; ++n) _Pragma("unroll") for (int k = 0; k < 2; ++k) \
;         acc[ai][bj][m][n] = mma16<Epi::I8>(Bt[n][k], At[m][k], acc[ai][bj][m][n]); __builtin_amdgcn_s_setprio(0); } while (0)
; #define PG8_WAIT_V(n) asm volatile("s_waitcnt vmcnt(" #n ")" ::: "memory")
; #define PG8_WAIT_L(n) asm volatile("s_waitcnt lgkmcnt(" #n ")" ::: "memory")
; #define PG8_BAR __builtin_amdgcn_s_barrier()
; #define PG8_SCHED __builtin_amdgcn_sched_barrier(0)
; template <class Epi, class Sched, bool ALIGN_EPI = false, bool SP2 = false>
; __device__ __forceinline__ void gemm_phase(PG8_LAS unsigned char* lds, const Gemm g, const Sched& S, const Epi& E) {
;     ...
;             const char* a1 = cA + (size_t)(t + 1) * kstep;
;             const char* a2 = last ? nA : cA + (size_t)(t + 2) * kstep; const char* b2 = last ? nB : cB + (size_t)(t + 2) * kstep;
;             const char* a3 = a2 + kstep; const char* b3 = b2 + kstep;
;             if (last && has_next) S.a_ready(nxt);
;             if constexpr (SP2) {
;             PG8_LDB(B0, 0, 0); PG8_LDB(B1, 0, 1); PG8_SCHED; PG8_LDA(At, 0, 0); PG8_STAGE(PG8_SA(1, 1), a1 + hstep, voffA);
;             PG8_WAIT_V(8); PG8_WAIT_L(0); PG8_BAR; PG8_MMA(0, 0, At, B0); PG8_MMA(0, 1, At, B1); PG8_BAR; PG8_SCHED;
;             PG8_LDA(At, 0, 1); PG8_STAGE(PG8_SB(0, 0), b2, voffB); PG8_STAGE(PG8_SB(0, 1), b2 + hstep, voffB); PG8_STAGE(PG8_SA(0, 0), a2, voffA);
;             PG8_WAIT_V(8); PG8_WAIT_L(0); PG8_BAR; PG8_MMA(1, 0, At, B0); PG8_MMA(1, 1, At, B1); PG8_BAR; PG8_SCHED;
.Lpeel385:
	s_add_u32 s70, s8, 0x100
	s_addc_u32 s71, s9, 0
	s_add_i32 s84, 0, 0x10000
	s_cmp_eq_u32 s5, 12
	s_cselect_b32 vcc_hi, s1, s71
	s_cselect_b32 vcc_lo, s7, s70
	v_add_u32_e32 v0, s84, v214
	s_cselect_b32 s83, s69, s68
	s_cselect_b32 s82, s81, s85
	s_add_i32 s10, 0, 0x14000
	ds_read_b128 v[44:47], v0
	ds_read_b128 v[52:55], v0 offset:1024
	ds_read_b128 v[60:63], v0 offset:2048
	ds_read_b128 v[64:67], v0 offset:3072
	v_add_u32_e32 v0, s10, v214
	ds_read_b128 v[84:87], v0
	ds_read_b128 v[88:91], v0 offset:1024
	ds_read_b128 v[92:95], v0 offset:2048
	ds_read_b128 v[100:103], v0 offset:3072
	s_add_i32 m0, s13, 0xc000
	ds_read_b128 v[124:127], v215
	ds_read_b128 v[128:131], v215 offset:1024
	ds_read_b128 v[140:143], v215 offset:2048
	ds_read_b128 v[188:191], v215 offset:3072
	ds_read_b128 v[192:195], v215 offset:4096
	ds_read_b128 v[196:199], v215 offset:5120
	ds_read_b128 v[216:219], v215 offset:6144
	ds_read_b128 v[220:223], v215 offset:7168
	global_load_lds_dwordx4 v184, s[8:9]
	s_add_i32 m0, s13, 0xe000
	s_nop 0
	global_load_lds_dwordx4 v186, s[8:9]
	s_waitcnt vmcnt(8)
	s_waitcnt lgkmcnt(0)
	s_barrier
	s_waitcnt lgkmcnt(0)
	v_mfma_i32_16x16x64_i8 v[172:175], v[44:47], v[124:127], 0
	v_mfma_i32_16x16x64_i8 v[164:167], v[60:63], v[124:127], 0
	v_mfma_i32_16x16x64_i8 v[160:163], v[60:63], v[140:143], 0
	v_mfma_i32_16x16x64_i8 v[168:171], v[44:47], v[140:143], 0
	v_mfma_i32_16x16x64_i8 v[156:159], v[44:47], v[192:195], 0
	v_mfma_i32_16x16x64_i8 v[152:155], v[60:63], v[192:195], 0
	v_mfma_i32_16x16x64_i8 v[144:147], v[60:63], v[216:219], 0
	v_mfma_i32_16x16x64_i8 v[148:151], v[44:47], v[216:219], 0
	v_mfma_i32_16x16x64_i8 v[172:175], v[52:55], v[128:131], v[172:175]
	v_mfma_i32_16x16x64_i8 v[164:167], v[64:67], v[128:131], v[164:167]
	v_mfma_i32_16x16x64_i8 v[160:163], v[64:67], v[188:191], v[160:163]
	v_mfma_i32_16x16x64_i8 v[168:171], v[52:55], v[188:191], v[168:171]
	v_mfma_i32_16x16x64_i8 v[156:159], v[52:55], v[196:199], v[156:159]
	v_mfma_i32_16x16x64_i8 v[152:155], v[64:67], v[196:199], v[152:155]
	v_mfma_i32_16x16x64_i8 v[144:147], v[64:67], v[220:223], v[144:147]
	v_mfma_i32_16x16x64_i8 v[148:151], v[52:55], v[220:223], v[148:151]
	v_mfma_i32_16x16x64_i8 v[136:139], v[84:87], v[124:127], 0
	v_mfma_i32_16x16x64_i8 v[120:123], v[92:95], v[124:127], 0
	v_mfma_i32_16x16x64_i8 v[116:119], v[92:95], v[140:143], 0
	v_mfma_i32_16x16x64_i8 v[108:111], v[92:95], v[192:195], 0
	v_mfma_i32_16x16x64_i8 v[112:115], v[84:87], v[192:195], 0
	v_mfma_i32_16x16x64_i8 v[104:107], v[84:87], v[216:219], 0
	v_mfma_i32_16x16x64_i8 v[96:99], v[92:95], v[216:219], 0
	v_mfma_i32_16x16x64_i8 v[136:139], v[88:91], v[128:131], v[136:139]
	v_mfma_i32_16x16x64_i8 v[120:123], v[100:103], v[128:131], v[120:123]
	v_mfma_i32_16x16x64_i8 v[116:119], v[100:103], v[188:191], v[116:119]
	v_mfma_i32_16x16x64_i8 v[108:111], v[100:103], v[196:199], v[108:111]
	v_mfma_i32_16x16x64_i8 v[112:115], v[88:91], v[196:199], v[112:115]
	v_mfma_i32_16x16x64_i8 v[104:107], v[88:91], v[220:223], v[104:107]
	v_mfma_i32_16x16x64_i8 v[96:99], v[100:103], v[220:223], v[96:99]
	v_mfma_i32_16x16x64_i8 v[124:127], v[84:87], v[140:143], 0
	v_mfma_i32_16x16x64_i8 v[124:127], v[88:91], v[188:191], v[124:127]
	s_barrier
	s_add_i32 s8, s84, s12
	s_mov_b32 m0, s8
	ds_read_b128 v[128:131], v215 offset:16384
	ds_read_b128 v[132:135], v215 offset:17408
	ds_read_b128 v[140:143], v215 offset:18432
	ds_read_b128 v[188:191], v215 offset:19456
	ds_read_b128 v[192:195], v215 offset:20480
	ds_read_b128 v[196:199], v215 offset:21504
	ds_read_b128 v[216:219], v215 offset:22528
	ds_read_b128 v[220:223], v215 offset:23552
	global_load_lds_dwordx4 v178, s[82:83]
	s_add_i32 m0, s8, 0x2000
	s_add_u32 s8, s82, 0x40000
	s_addc_u32 s9, s83, 0
	s_add_i32 s10, s10, s12
	global_load_lds_dwordx4 v182, s[82:83]
	s_mov_b32 m0, s10
	s_nop 0
	global_load_lds_dwordx4 v178, s[8:9]
	s_add_i32 m0, s10, 0x2000
	s_nop 0
	global_load_lds_dwordx4 v182, s[8:9]
	s_mov_b32 m0, s13
	s_nop 0
	global_load_lds_dwordx4 v176, vcc
	s_mov_b32 m0, s66
	s_nop 0
	global_load_lds_dwordx4 v180, vcc
	s_waitcnt vmcnt(8)
	s_waitcnt lgkmcnt(0)
	s_barrier
	s_waitcnt lgkmcnt(0)
	v_mfma_i32_16x16x64_i8 v[80:83], v[44:47], v[128:131], 0
	v_mfma_i32_16x16x64_i8 v[72:75], v[60:63], v[128:131], 0
	v_mfma_i32_16x16x64_i8 v[68:71], v[60:63], v[140:143], 0
	v_mfma_i32_16x16x64_i8 v[76:79], v[44:47], v[140:143], 0
	v_mfma_i32_16x16x64_i8 v[56:59], v[44:47], v[192:195], 0
	v_mfma_i32_16x16x64_i8 v[48:51], v[60:63], v[192:195], 0
	v_mfma_i32_16x16x64_i8 v[36:39], v[60:63], v[216:219], 0
	v_mfma_i32_16x16x64_i8 v[40:43], v[44:47], v[216:219], 0
	v_mfma_i32_16x16x64_i8 v[80:83], v[52:55], v[132:135], v[80:83]
	v_mfma_i32_16x16x64_i8 v[72:75], v[64:67], v[132:135], v[72:75]
	v_mfma_i32_16x16x64_i8 v[68:71], v[64:67], v[188:191], v[68:71]
	v_mfma_i32_16x16x64_i8 v[76:79], v[52:55], v[188:191], v[76:79]
	v_mfma_i32_16x16x64_i8 v[56:59], v[52:55], v[196:199], v[56:59]
	v_mfma_i32_16x16x64_i8 v[48:51], v[64:67], v[196:199], v[48:51]
	v_mfma_i32_16x16x64_i8 v[36:39], v[64:67], v[220:223], v[36:39]
	v_mfma_i32_16x16x64_i8 v[40:43], v[52:55], v[220:223], v[40:43]
	v_mfma_i32_16x16x64_i8 v[32:35], v[84:87], v[128:131], 0
	v_mfma_i32_16x16x64_i8 v[24:27], v[92:95], v[128:131], 0
	v_mfma_i32_16x16x64_i8 v[20:23], v[92:95], v[140:143], 0
	v_mfma_i32_16x16x64_i8 v[28:31], v[84:87], v[140:143], 0
	v_mfma_i32_16x16x64_i8 v[16:19], v[84:87], v[192:195], 0
	v_mfma_i32_16x16x64_i8 v[12:15], v[92:95], v[192:195], 0
	v_mfma_i32_16x16x64_i8 v[2:5], v[92:95], v[216:219], 0
	v_mfma_i32_16x16x64_i8 v[8:11], v[84:87], v[216:219], 0
	v_mfma_i32_16x16x64_i8 v[32:35], v[88:91], v[132:135], v[32:35]
	v_mfma_i32_16x16x64_i8 v[24:27], v[100:103], v[132:135], v[24:27]
	v_mfma_i32_16x16x64_i8 v[20:23], v[100:103], v[188:191], v[20:23]
	v_mfma_i32_16x16x64_i8 v[28:31], v[88:91], v[188:191], v[28:31]
	v_mfma_i32_16x16x64_i8 v[16:19], v[88:91], v[196:199], v[16:19]
	v_mfma_i32_16x16x64_i8 v[12:15], v[100:103], v[196:199], v[12:15]
	v_mfma_i32_16x16x64_i8 v[2:5], v[100:103], v[220:223], v[2:5]
	v_mfma_i32_16x16x64_i8 v[8:11], v[88:91], v[220:223], v[8:11]
	s_barrier
; #define PG8_STAGE(bufoff, gbase, voff) do { _Pragma("unroll") for (int _i = 0; _i < 2; ++_i) \
;         __builtin_amdgcn_global_load_lds((const unsigned*)((const char*)(gbase) + (voff)[_i]), (PG8_LAS unsigned*)(lds + (bufoff) + ldsw + _i * 8192), 16, 0, 0); } while (0)
; #define PG8_LDA(dst, b, h) do { _Pragma("unroll") for (int m = 0; m < 4; ++m) _Pragma("unroll") for (int k = 0; k < 2; ++k) dst[m][k] = *(const PG8_LAS bf16x8*)(lds + PG8_SA(b, h) + aoff + m * 2048 + k * 1024); } while (0)
; #define PG8_LDB(dst, b, h) do { _Pragma("unroll") for (int n = 0; n < 2; ++n) _Pragma("unroll") for (int k = 0; k < 2; ++k) dst[n][k] = *(const PG8_LAS bf16x8*)(lds + PG8_SB(b, h) + boff + n * 2048 + k * 1024); } while (0)
; #define PG8_MMA(ai, bj, At, Bt) do { __builtin_amdgcn_s_setprio(1); _Pragma("unroll") for (int m = 0; m < 4; ++m) _Pragma("unroll") for (int n = 0; n < 2; ++n) _Pragma("unroll") for (int k = 0; k < 2; ++k) \
;         acc[ai][bj][m][n] = mma16<Epi::I8>(Bt[n][k], At[m][k], acc[ai][bj][m][n]); __builtin_amdgcn_s_setprio(0); } while (0)
; #define PG8_WAIT_V(n) asm volatile("s_waitcnt vmcnt(" #n ")" ::: "memory")
; #define PG8_WAIT_L(n) asm volatile("s_waitcnt lgkmcnt(" #n ")" ::: "memory")
; #define PG8_BAR __builtin_amdgcn_s_barrier()
; #define PG8_SCHED __builtin_amdgcn_sched_barrier(0)
; template <class Epi, class Sched, bool ALIGN_EPI = false, bool SP2 = false>
; __device__ __forceinline__ void gemm_phase(PG8_LAS unsigned char* lds, const Gemm g, const Sched& S, const Epi& E) {
;     ...
;             PG8_LDB(B0, 1, 0); PG8_LDB(B1, 1, 1); PG8_SCHED; PG8_LDA(At, 1, 0); PG8_STAGE(PG8_SA(0, 1), a2 + hstep, voffA);
;             PG8_WAIT_V(8); PG8_WAIT_L(0); PG8_BAR; PG8_MMA(0, 0, At, B0); PG8_MMA(0, 1, At, B1); PG8_BAR; PG8_SCHED;
;             PG8_LDA(At, 1, 1); PG8_STAGE(PG8_SB(1, 0), b3, voffB); PG8_STAGE(PG8_SB(1, 1), b3 + hstep, voffB); PG8_STAGE(PG8_SA(1, 0), a3, voffA);
;             PG8_WAIT_V(8); PG8_WAIT_L(0); PG8_BAR; PG8_MMA(1, 0, At, B0); PG8_MMA(1, 1, At, B1); PG8_BAR; PG8_SCHED;
	s_add_i32 s10, 0, 0x18000
	v_add_u32_e32 v0, s10, v214
	s_add_i32 s11, 0, 0x1c000
	ds_read_b128 v[44:47], v0
	ds_read_b128 v[52:55], v0 offset:1024
	ds_read_b128 v[60:63], v0 offset:2048
	ds_read_b128 v[64:67], v0 offset:3072
	v_add_u32_e32 v0, s11, v214
	ds_read_b128 v[84:87], v0
	ds_read_b128 v[88:91], v0 offset:1024
	ds_read_b128 v[92:95], v0 offset:2048
	ds_read_b128 v[100:103], v0 offset:3072
	s_add_u32 s8, vcc_lo, 0x40000
	s_addc_u32 s9, vcc_hi, 0
	s_mov_b32 m0, s67
	ds_read_b128 v[128:131], v215 offset:32768
	ds_read_b128 v[132:135], v215 offset:33792
	ds_read_b128 v[140:143], v215 offset:34816
	ds_read_b128 v[188:191], v215 offset:35840
	ds_read_b128 v[192:195], v215 offset:36864
	ds_read_b128 v[196:199], v215 offset:37888
	ds_read_b128 v[216:219], v215 offset:38912
	ds_read_b128 v[220:223], v215 offset:39936
	global_load_lds_dwordx4 v176, s[8:9]
	s_mov_b32 m0, s80
	s_nop 0
	global_load_lds_dwordx4 v180, s[8:9]
	s_waitcnt vmcnt(8)
	s_waitcnt lgkmcnt(0)
	s_barrier
	s_waitcnt lgkmcnt(0)
	v_mfma_i32_16x16x64_i8 v[172:175], v[44:47], v[128:131], v[172:175]
	v_mfma_i32_16x16x64_i8 v[164:167], v[60:63], v[128:131], v[164:167]
	v_mfma_i32_16x16x64_i8 v[160:163], v[60:63], v[140:143], v[160:163]
	v_mfma_i32_16x16x64_i8 v[168:171], v[44:47], v[140:143], v[168:171]
	v_mfma_i32_16x16x64_i8 v[156:159], v[44:47], v[192:195], v[156:159]
	v_mfma_i32_16x16x64_i8 v[152:155], v[60:63], v[192:195], v[152:155]
	v_mfma_i32_16x16x64_i8 v[144:147], v[60:63], v[216:219], v[144:147]
	v_mfma_i32_16x16x64_i8 v[148:151], v[44:47], v[216:219], v[148:151]
	v_mfma_i32_16x16x64_i8 v[172:175], v[52:55], v[132:135], v[172:175]
	v_mfma_i32_16x16x64_i8 v[164:167], v[64:67], v[132:135], v[164:167]
	v_mfma_i32_16x16x64_i8 v[160:163], v[64:67], v[188:191], v[160:163]
	v_mfma_i32_16x16x64_i8 v[168:171], v[52:55], v[188:191], v[168:171]
	v_mfma_i32_16x16x64_i8 v[156:159], v[52:55], v[196:199], v[156:159]
	v_mfma_i32_16x16x64_i8 v[152:155], v[64:67], v[196:199], v[152:155]
	v_mfma_i32_16x16x64_i8 v[144:147], v[64:67], v[220:223], v[144:147]
	v_mfma_i32_16x16x64_i8 v[148:151], v[52:55], v[220:223], v[148:151]
	v_mfma_i32_16x16x64_i8 v[136:139], v[84:87], v[128:131], v[136:139]
	v_mfma_i32_16x16x64_i8 v[120:123], v[92:95], v[128:131], v[120:123]
	v_mfma_i32_16x16x64_i8 v[116:119], v[92:95], v[140:143], v[116:119]
	v_mfma_i32_16x16x64_i8 v[124:127], v[84:87], v[140:143], v[124:127]
	v_mfma_i32_16x16x64_i8 v[112:115], v[84:87], v[192:195], v[112:115]
	v_mfma_i32_16x16x64_i8 v[108:111], v[92:95], v[192:195], v[108:111]
	v_mfma_i32_16x16x64_i8 v[96:99], v[92:95], v[216:219], v[96:99]
	v_mfma_i32_16x16x64_i8 v[104:107], v[84:87], v[216:219], v[104:107]
	v_mfma_i32_16x16x64_i8 v[136:139], v[88:91], v[132:135], v[136:139]
	v_mfma_i32_16x16x64_i8 v[120:123], v[100:103], v[132:135], v[120:123]
	v_mfma_i32_16x16x64_i8 v[116:119], v[100:103], v[188:191], v[116:119]
	v_mfma_i32_16x16x64_i8 v[132:135], v[88:91], v[188:191], v[124:127]
	v_mfma_i32_16x16x64_i8 v[112:115], v[88:91], v[196:199], v[112:115]
	v_mfma_i32_16x16x64_i8 v[108:111], v[100:103], v[196:199], v[108:111]
	v_mfma_i32_16x16x64_i8 v[96:99], v[100:103], v[220:223], v[96:99]
	v_mfma_i32_16x16x64_i8 v[104:107], v[88:91], v[220:223], v[104:107]
	s_barrier
	s_add_i32 s8, s10, s12
	s_add_u32 s98, s82, 0x80
	s_addc_u32 s99, s83, 0
	s_add_u32 s100, vcc_lo, 0x80
	s_addc_u32 s101, vcc_hi, 0
	s_mov_b32 m0, s8
	ds_read_b128 v[124:127], v215 offset:49152
	ds_read_b128 v[128:131], v215 offset:50176
	ds_read_b128 v[140:143], v215 offset:51200
	ds_read_b128 v[188:191], v215 offset:52224
	ds_read_b128 v[192:195], v215 offset:53248
	ds_read_b128 v[196:199], v215 offset:54272
	ds_read_b128 v[216:219], v215 offset:55296
	ds_read_b128 v[220:223], v215 offset:56320
	global_load_lds_dwordx4 v178, s[98:99]
	s_add_i32 m0, s8, 0x2000
	s_add_u32 s8, s82, 0x40080
	s_addc_u32 s9, s83, 0
	s_add_i32 s10, s11, s12
	global_load_lds_dwordx4 v182, s[98:99]
	s_mov_b32 m0, s10
	s_nop 0
	global_load_lds_dwordx4 v178, s[8:9]
	s_add_i32 m0, s10, 0x2000
	s_nop 0
	global_load_lds_dwordx4 v182, s[8:9]
	s_mov_b32 m0, s58
	s_nop 0
	global_load_lds_dwordx4 v176, s[100:101]
	s_mov_b32 m0, s4
	s_nop 0
	global_load_lds_dwordx4 v180, s[100:101]
	s_waitcnt vmcnt(8)
	s_waitcnt lgkmcnt(0)
	s_barrier
	s_waitcnt lgkmcnt(0)
	v_mfma_i32_16x16x64_i8 v[80:83], v[44:47], v[124:127], v[80:83]
	v_mfma_i32_16x16x64_i8 v[72:75], v[60:63], v[124:127], v[72:75]
	v_mfma_i32_16x16x64_i8 v[68:71], v[60:63], v[140:143], v[68:71]
	v_mfma_i32_16x16x64_i8 v[76:79], v[44:47], v[140:143], v[76:79]
	v_mfma_i32_16x16x64_i8 v[56:59], v[44:47], v[192:195], v[56:59]
	v_mfma_i32_16x16x64_i8 v[48:51], v[60:63], v[192:195], v[48:51]
	v_mfma_i32_16x16x64_i8 v[36:39], v[60:63], v[216:219], v[36:39]
	v_mfma_i32_16x16x64_i8 v[40:43], v[44:47], v[216:219], v[40:43]
	v_mfma_i32_16x16x64_i8 v[80:83], v[52:55], v[128:131], v[80:83]
	v_mfma_i32_16x16x64_i8 v[72:75], v[64:67], v[128:131], v[72:75]
	v_mfma_i32_16x16x64_i8 v[68:71], v[64:67], v[188:191], v[68:71]
	v_mfma_i32_16x16x64_i8 v[76:79], v[52:55], v[188:191], v[76:79]
	v_mfma_i32_16x16x64_i8 v[56:59], v[52:55], v[196:199], v[56:59]
	v_mfma_i32_16x16x64_i8 v[48:51], v[64:67], v[196:199], v[48:51]
	v_mfma_i32_16x16x64_i8 v[36:39], v[64:67], v[220:223], v[36:39]
	v_mfma_i32_16x16x64_i8 v[40:43], v[52:55], v[220:223], v[40:43]
	v_mfma_i32_16x16x64_i8 v[32:35], v[84:87], v[124:127], v[32:35]
	v_mfma_i32_16x16x64_i8 v[24:27], v[92:95], v[124:127], v[24:27]
	v_mfma_i32_16x16x64_i8 v[20:23], v[92:95], v[140:143], v[20:23]
	v_mfma_i32_16x16x64_i8 v[28:31], v[84:87], v[140:143], v[28:31]
	v_mfma_i32_16x16x64_i8 v[16:19], v[84:87], v[192:195], v[16:19]
	v_mfma_i32_16x16x64_i8 v[12:15], v[92:95], v[192:195], v[12:15]
	v_mfma_i32_16x16x64_i8 v[2:5], v[92:95], v[216:219], v[2:5]
	v_mfma_i32_16x16x64_i8 v[6:9], v[84:87], v[216:219], v[8:11]
	v_mfma_i32_16x16x64_i8 v[32:35], v[88:91], v[128:131], v[32:35]
	v_mfma_i32_16x16x64_i8 v[24:27], v[100:103], v[128:131], v[24:27]
	v_mfma_i32_16x16x64_i8 v[20:23], v[100:103], v[188:191], v[20:23]
	v_mfma_i32_16x16x64_i8 v[28:31], v[88:91], v[188:191], v[28:31]
	v_mfma_i32_16x16x64_i8 v[16:19], v[88:91], v[196:199], v[16:19]
	v_mfma_i32_16x16x64_i8 v[12:15], v[100:103], v[196:199], v[12:15]
	v_mfma_i32_16x16x64_i8 v[8:11], v[88:91], v[220:223], v[6:9]
	v_mfma_i32_16x16x64_i8 v[4:7], v[100:103], v[220:223], v[2:5]
	s_barrier
	s_add_i32 s5, s5, 2
	s_add_u32 s85, s85, 0x100
	s_addc_u32 s68, s68, 0
	s_cmp_gt_u32 s5, 13
	s_mov_b64 s[8:9], s[70:71]
	s_cbranch_scc0 .LBB0_385
	s_branch .Lpeelx385
; #define PG8_STAGE(bufoff, gbase, voff) do { _Pragma("unroll") for (int _i = 0; _i < 2; ++_i) \
;         __builtin_amdgcn_global_load_lds((const unsigned*)((const char*)(gbase) + (voff)[_i]), (PG8_LAS unsigned*)(lds + (bufoff) + ldsw + _i * 8192), 16, 0, 0); } while (0)
; #define PG8_LDA(dst, b, h) do { _Pragma("unroll") for (int m = 0; m < 4; ++m) _Pragma("unroll") for (int k = 0; k < 2; ++k) dst[m][k] = *(const PG8_LAS bf16x8*)(lds + PG8_SA(b, h) + aoff + m * 2048 + k * 1024); } while (0)
; #define PG8_LDB(dst, b, h) do { _Pragma("unroll") for (int n = 0; n < 2; ++n) _Pragma("unroll") for (int k = 0; k < 2; ++k) dst[n][k] = *(const PG8_LAS bf16x8*)(lds + PG8_SB(b, h) + boff + n * 2048 + k * 1024); } while (0)
; #define PG8_MMA(ai, bj, At, Bt) do { __builtin_amdgcn_s_setprio(1); _Pragma("unroll") for (int m = 0; m < 4; ++m) _Pragma("unroll") for (int n = 0; n < 2; ++n) _Pragma("unroll") for (int k = 0; k < 2; ++k) \
;         acc[ai][bj][m][n] = mma16<Epi::I8>(Bt[n][k], At[m][k], acc[ai][bj][m][n]); __builtin_amdgcn_s_setprio(0); } while (0)
; #define PG8_WAIT_V(n) asm volatile("s_waitcnt vmcnt(" #n ")" ::: "memory")
; #define PG8_WAIT_L(n) asm volatile("s_waitcnt lgkmcnt(" #n ")" ::: "memory")
; #define PG8_BAR __builtin_amdgcn_s_barrier()
; #define PG8_SCHED __builtin_amdgcn_sched_barrier(0)
; template <class Epi, class Sched, bool ALIGN_EPI = false, bool SP2 = false>
; __device__ __forceinline__ void gemm_phase(PG8_LAS unsigned char* lds, const Gemm g, const Sched& S, const Epi& E) {
;     ...
;             const char* a1 = cA + (size_t)(t + 1) * kstep;
;             const char* a2 = last ? nA : cA + (size_t)(t + 2) * kstep; const char* b2 = last ? nB : cB + (size_t)(t + 2) * kstep;
;             const char* a3 = a2 + kstep; const char* b3 = b2 + kstep;
;             if (last && has_next) S.a_ready(nxt);
;             if constexpr (SP2) {
;             PG8_LDB(B0, 0, 0); PG8_LDB(B1, 0, 1); PG8_SCHED; PG8_LDA(At, 0, 0); PG8_STAGE(PG8_SA(1, 1), a1 + hstep, voffA);
;             PG8_WAIT_V(8); PG8_WAIT_L(0); PG8_BAR; PG8_MMA(0, 0, At, B0); PG8_MMA(0, 1, At, B1); PG8_BAR; PG8_SCHED;
;             PG8_LDA(At, 0, 1); PG8_STAGE(PG8_SB(0, 0), b2, voffB); PG8_STAGE(PG8_SB(0, 1), b2 + hstep, voffB); PG8_STAGE(PG8_SA(0, 0), a2, voffA);
;             PG8_WAIT_V(8); PG8_WAIT_L(0); PG8_BAR; PG8_MMA(1, 0, At, B0); PG8_MMA(1, 1, At, B1); PG8_BAR; PG8_SCHED;
.LBB0_385:
	s_add_u32 s70, s8, 0x100
	s_addc_u32 s71, s9, 0
	s_add_i32 s84, 0, 0x10000
	s_cmp_eq_u32 s5, 12
	s_cselect_b32 vcc_hi, s1, s71
	s_cselect_b32 vcc_lo, s7, s70
	v_add_u32_e32 v0, s84, v214
	s_cselect_b32 s83, s69, s68
	s_cselect_b32 s82, s81, s85
	s_add_i32 s10, 0, 0x14000
	ds_read_b128 v[44:47], v0
	ds_read_b128 v[52:55], v0 offset:1024
	ds_read_b128 v[60:63], v0 offset:2048
	ds_read_b128 v[64:67], v0 offset:3072
	v_add_u32_e32 v0, s10, v214
	ds_read_b128 v[84:87], v0
	ds_read_b128 v[88:91], v0 offset:1024
	ds_read_b128 v[92:95], v0 offset:2048
	ds_read_b128 v[100:103], v0 offset:3072
	s_add_i32 m0, s13, 0xc000
	ds_read_b128 v[124:127], v215
	ds_read_b128 v[128:131], v215 offset:1024
	ds_read_b128 v[140:143], v215 offset:2048
	ds_read_b128 v[188:191], v215 offset:3072
	ds_read_b128 v[192:195], v215 offset:4096
	ds_read_b128 v[196:199], v215 offset:5120
	ds_read_b128 v[216:219], v215 offset:6144
	ds_read_b128 v[220:223], v215 offset:7168
	global_load_lds_dwordx4 v184, s[8:9]
	s_add_i32 m0, s13, 0xe000
	s_nop 0
	global_load_lds_dwordx4 v186, s[8:9]
	s_waitcnt vmcnt(8)
	s_waitcnt lgkmcnt(0)
	s_barrier
	s_waitcnt lgkmcnt(0)
	v_mfma_i32_16x16x64_i8 v[172:175], v[44:47], v[124:127], v[172:175]
	v_mfma_i32_16x16x64_i8 v[164:167], v[60:63], v[124:127], v[164:167]
	v_mfma_i32_16x16x64_i8 v[160:163], v[60:63], v[140:143], v[160:163]
	v_mfma_i32_16x16x64_i8 v[168:171], v[44:47], v[140:143], v[168:171]
	v_mfma_i32_16x16x64_i8 v[156:159], v[44:47], v[192:195], v[156:159]
	v_mfma_i32_16x16x64_i8 v[152:155], v[60:63], v[192:195], v[152:155]
	v_mfma_i32_16x16x64_i8 v[144:147], v[60:63], v[216:219], v[144:147]
	v_mfma_i32_16x16x64_i8 v[148:151], v[44:47], v[216:219], v[148:151]
	v_mfma_i32_16x16x64_i8 v[172:175], v[52:55], v[128:131], v[172:175]
	v_mfma_i32_16x16x64_i8 v[164:167], v[64:67], v[128:131], v[164:167]
	v_mfma_i32_16x16x64_i8 v[160:163], v[64:67], v[188:191], v[160:163]
	v_mfma_i32_16x16x64_i8 v[168:171], v[52:55], v[188:191], v[168:171]
	v_mfma_i32_16x16x64_i8 v[156:159], v[52:55], v[196:199], v[156:159]
	v_mfma_i32_16x16x64_i8 v[152:155], v[64:67], v[196:199], v[152:155]
	v_mfma_i32_16x16x64_i8 v[144:147], v[64:67], v[220:223], v[144:147]
	v_mfma_i32_16x16x64_i8 v[148:151], v[52:55], v[220:223], v[148:151]
	v_mfma_i32_16x16x64_i8 v[136:139], v[84:87], v[124:127], v[136:139]
	v_mfma_i32_16x16x64_i8 v[120:123], v[92:95], v[124:127], v[120:123]
	v_mfma_i32_16x16x64_i8 v[116:119], v[92:95], v[140:143], v[116:119]
	v_mfma_i32_16x16x64_i8 v[108:111], v[92:95], v[192:195], v[108:111]
	v_mfma_i32_16x16x64_i8 v[112:115], v[84:87], v[192:195], v[112:115]
	v_mfma_i32_16x16x64_i8 v[104:107], v[84:87], v[216:219], v[104:107]
	v_mfma_i32_16x16x64_i8 v[96:99], v[92:95], v[216:219], v[96:99]
	v_mfma_i32_16x16x64_i8 v[136:139], v[88:91], v[128:131], v[136:139]
	v_mfma_i32_16x16x64_i8 v[120:123], v[100:103], v[128:131], v[120:123]
	v_mfma_i32_16x16x64_i8 v[116:119], v[100:103], v[188:191], v[116:119]
	v_mfma_i32_16x16x64_i8 v[108:111], v[100:103], v[196:199], v[108:111]
	v_mfma_i32_16x16x64_i8 v[112:115], v[88:91], v[196:199], v[112:115]
	v_mfma_i32_16x16x64_i8 v[104:107], v[88:91], v[220:223], v[104:107]
	v_mfma_i32_16x16x64_i8 v[96:99], v[100:103], v[220:223], v[96:99]
	v_mfma_i32_16x16x64_i8 v[124:127], v[84:87], v[140:143], v[132:135]
	v_mfma_i32_16x16x64_i8 v[124:127], v[88:91], v[188:191], v[124:127]
	s_barrier
	s_add_i32 s8, s84, s12
	s_mov_b32 m0, s8
	ds_read_b128 v[128:131], v215 offset:16384
	ds_read_b128 v[132:135], v215 offset:17408
	ds_read_b128 v[140:143], v215 offset:18432
	ds_read_b128 v[188:191], v215 offset:19456
	ds_read_b128 v[192:195], v215 offset:20480
	ds_read_b128 v[196:199], v215 offset:21504
	ds_read_b128 v[216:219], v215 offset:22528
	ds_read_b128 v[220:223], v215 offset:23552
	global_load_lds_dwordx4 v178, s[82:83]
	s_add_i32 m0, s8, 0x2000
	s_add_u32 s8, s82, 0x40000
	s_addc_u32 s9, s83, 0
	s_add_i32 s10, s10, s12
	global_load_lds_dwordx4 v182, s[82:83]
	s_mov_b32 m0, s10
	s_nop 0
	global_load_lds_dwordx4 v178, s[8:9]
	s_add_i32 m0, s10, 0x2000
	s_nop 0
	global_load_lds_dwordx4 v182, s[8:9]
	s_mov_b32 m0, s13
	s_nop 0
	global_load_lds_dwordx4 v176, vcc
	s_mov_b32 m0, s66
	s_nop 0
	global_load_lds_dwordx4 v180, vcc
	s_waitcnt vmcnt(8)
	s_waitcnt lgkmcnt(0)
	s_barrier
	s_waitcnt lgkmcnt(0)
	v_mfma_i32_16x16x64_i8 v[80:83], v[44:47], v[128:131], v[80:83]
	v_mfma_i32_16x16x64_i8 v[72:75], v[60:63], v[128:131], v[72:75]
	v_mfma_i32_16x16x64_i8 v[68:71], v[60:63], v[140:143], v[68:71]
	v_mfma_i32_16x16x64_i8 v[76:79], v[44:47], v[140:143], v[76:79]
	v_mfma_i32_16x16x64_i8 v[56:59], v[44:47], v[192:195], v[56:59]
	v_mfma_i32_16x16x64_i8 v[48:51], v[60:63], v[192:195], v[48:51]
	v_mfma_i32_16x16x64_i8 v[36:39], v[60:63], v[216:219], v[36:39]
	v_mfma_i32_16x16x64_i8 v[40:43], v[44:47], v[216:219], v[40:43]
	v_mfma_i32_16x16x64_i8 v[80:83], v[52:55], v[132:135], v[80:83]
	v_mfma_i32_16x16x64_i8 v[72:75], v[64:67], v[132:135], v[72:75]
	v_mfma_i32_16x16x64_i8 v[68:71], v[64:67], v[188:191], v[68:71]
	v_mfma_i32_16x16x64_i8 v[76:79], v[52:55], v[188:191], v[76:79]
	v_mfma_i32_16x16x64_i8 v[56:59], v[52:55], v[196:199], v[56:59]
	v_mfma_i32_16x16x64_i8 v[48:51], v[64:67], v[196:199], v[48:51]
	v_mfma_i32_16x16x64_i8 v[36:39], v[64:67], v[220:223], v[36:39]
	v_mfma_i32_16x16x64_i8 v[40:43], v[52:55], v[220:223], v[40:43]
	v_mfma_i32_16x16x64_i8 v[32:35], v[84:87], v[128:131], v[32:35]
	v_mfma_i32_16x16x64_i8 v[24:27], v[92:95], v[128:131], v[24:27]
	v_mfma_i32_16x16x64_i8 v[20:23], v[92:95], v[140:143], v[20:23]
	v_mfma_i32_16x16x64_i8 v[28:31], v[84:87], v[140:143], v[28:31]
	v_mfma_i32_16x16x64_i8 v[16:19], v[84:87], v[192:195], v[16:19]
	v_mfma_i32_16x16x64_i8 v[12:15], v[92:95], v[192:195], v[12:15]
	v_mfma_i32_16x16x64_i8 v[2:5], v[92:95], v[216:219], v[4:7]
	v_mfma_i32_16x16x64_i8 v[8:11], v[84:87], v[216:219], v[8:11]
	v_mfma_i32_16x16x64_i8 v[32:35], v[88:91], v[132:135], v[32:35]
	v_mfma_i32_16x16x64_i8 v[24:27], v[100:103], v[132:135], v[24:27]
	v_mfma_i32_16x16x64_i8 v[20:23], v[100:103], v[188:191], v[20:23]
	v_mfma_i32_16x16x64_i8 v[28:31], v[88:91], v[188:191], v[28:31]
	v_mfma_i32_16x16x64_i8 v[16:19], v[88:91], v[196:199], v[16:19]
	v_mfma_i32_16x16x64_i8 v[12:15], v[100:103], v[196:199], v[12:15]
	v_mfma_i32_16x16x64_i8 v[2:5], v[100:103], v[220:223], v[2:5]
	v_mfma_i32_16x16x64_i8 v[8:11], v[88:91], v[220:223], v[8:11]
	s_barrier
; #define PG8_STAGE(bufoff, gbase, voff) do { _Pragma("unroll") for (int _i = 0; _i < 2; ++_i) \
;         __builtin_amdgcn_global_load_lds((const unsigned*)((const char*)(gbase) + (voff)[_i]), (PG8_LAS unsigned*)(lds + (bufoff) + ldsw + _i * 8192), 16, 0, 0); } while (0)
; #define PG8_LDA(dst, b, h) do { _Pragma("unroll") for (int m = 0; m < 4; ++m) _Pragma("unroll") for (int k = 0; k < 2; ++k) dst[m][k] = *(const PG8_LAS bf16x8*)(lds + PG8_SA(b, h) + aoff + m * 2048 + k * 1024); } while (0)
; #define PG8_LDB(dst, b, h) do { _Pragma("unroll") for (int n = 0; n < 2; ++n) _Pragma("unroll") for (int k = 0; k < 2; ++k) dst[n][k] = *(const PG8_LAS bf16x8*)(lds + PG8_SB(b, h) + boff + n * 2048 + k * 1024); } while (0)
; #define PG8_MMA(ai, bj, At, Bt) do { __builtin_amdgcn_s_setprio(1); _Pragma("unroll") for (int m = 0; m < 4; ++m) _Pragma("unroll") for (int n = 0; n < 2; ++n) _Pragma("unroll") for (int k = 0; k < 2; ++k) \
;         acc[ai][bj][m][n] = mma16<Epi::I8>(Bt[n][k], At[m][k], acc[ai][bj][m][n]); __builtin_amdgcn_s_setprio(0); } while (0)
; #define PG8_WAIT_V(n) asm volatile("s_waitcnt vmcnt(" #n ")" ::: "memory")
; #define PG8_WAIT_L(n) asm volatile("s_waitcnt lgkmcnt(" #n ")" ::: "memory")
; #define PG8_BAR __builtin_amdgcn_s_barrier()
; #define PG8_SCHED __builtin_amdgcn_sched_barrier(0)
; template <class Epi, class Sched, bool ALIGN_EPI = false, bool SP2 = false>
; __device__ __forceinline__ void gemm_phase(PG8_LAS unsigned char* lds, const Gemm g, const Sched& S, const Epi& E) {
;     ...
;             PG8_LDB(B0, 1, 0); PG8_LDB(B1, 1, 1); PG8_SCHED; PG8_LDA(At, 1, 0); PG8_STAGE(PG8_SA(0, 1), a2 + hstep, voffA);
;             PG8_WAIT_V(8); PG8_WAIT_L(0); PG8_BAR; PG8_MMA(0, 0, At, B0); PG8_MMA(0, 1, At, B1); PG8_BAR; PG8_SCHED;
;             PG8_LDA(At, 1, 1); PG8_STAGE(PG8_SB(1, 0), b3, voffB); PG8_STAGE(PG8_SB(1, 1), b3 + hstep, voffB); PG8_STAGE(PG8_SA(1, 0), a3, voffA);
;             PG8_WAIT_V(8); PG8_WAIT_L(0); PG8_BAR; PG8_MMA(1, 0, At, B0); PG8_MMA(1, 1, At, B1); PG8_BAR; PG8_SCHED;
	s_add_i32 s10, 0, 0x18000
	v_add_u32_e32 v0, s10, v214
	s_add_i32 s11, 0, 0x1c000
	ds_read_b128 v[44:47], v0
	ds_read_b128 v[52:55], v0 offset:1024
	ds_read_b128 v[60:63], v0 offset:2048
	ds_read_b128 v[64:67], v0 offset:3072
	v_add_u32_e32 v0, s11, v214
	ds_read_b128 v[84:87], v0
	ds_read_b128 v[88:91], v0 offset:1024
	ds_read_b128 v[92:95], v0 offset:2048
	ds_read_b128 v[100:103], v0 offset:3072
	s_add_u32 s8, vcc_lo, 0x40000
	s_addc_u32 s9, vcc_hi, 0
	s_mov_b32 m0, s67
	ds_read_b128 v[128:131], v215 offset:32768
	ds_read_b128 v[132:135], v215 offset:33792
	ds_read_b128 v[140:143], v215 offset:34816
	ds_read_b128 v[188:191], v215 offset:35840
	ds_read_b128 v[192:195], v215 offset:36864
	ds_read_b128 v[196:199], v215 offset:37888
	ds_read_b128 v[216:219], v215 offset:38912
	ds_read_b128 v[220:223], v215 offset:39936
	global_load_lds_dwordx4 v176, s[8:9]
	s_mov_b32 m0, s80
	s_nop 0
	global_load_lds_dwordx4 v180, s[8:9]
	s_waitcnt vmcnt(8)
	s_waitcnt lgkmcnt(0)
	s_barrier
	s_waitcnt lgkmcnt(0)
	v_mfma_i32_16x16x64_i8 v[172:175], v[44:47], v[128:131], v[172:175]
	v_mfma_i32_16x16x64_i8 v[164:167], v[60:63], v[128:131], v[164:167]
	v_mfma_i32_16x16x64_i8 v[160:163], v[60:63], v[140:143], v[160:163]
	v_mfma_i32_16x16x64_i8 v[168:171], v[44:47], v[140:143], v[168:171]
	v_mfma_i32_16x16x64_i8 v[156:159], v[44:47], v[192:195], v[156:159]
	v_mfma_i32_16x16x64_i8 v[152:155], v[60:63], v[192:195], v[152:155]
	v_mfma_i32_16x16x64_i8 v[144:147], v[60:63], v[216:219], v[144:147]
	v_mfma_i32_16x16x64_i8 v[148:151], v[44:47], v[216:219], v[148:151]
	v_mfma_i32_16x16x64_i8 v[172:175], v[52:55], v[132:135], v[172:175]
	v_mfma_i32_16x16x64_i8 v[164:167], v[64:67], v[132:135], v[164:167]
	v_mfma_i32_16x16x64_i8 v[160:163], v[64:67], v[188:191], v[160:163]
	v_mfma_i32_16x16x64_i8 v[168:171], v[52:55], v[188:191], v[168:171]
	v_mfma_i32_16x16x64_i8 v[156:159], v[52:55], v[196:199], v[156:159]
	v_mfma_i32_16x16x64_i8 v[152:155], v[64:67], v[196:199], v[152:155]
	v_mfma_i32_16x16x64_i8 v[144:147], v[64:67], v[220:223], v[144:147]
	v_mfma_i32_16x16x64_i8 v[148:151], v[52:55], v[220:223], v[148:151]
	v_mfma_i32_16x16x64_i8 v[136:139], v[84:87], v[128:131], v[136:139]
	v_mfma_i32_16x16x64_i8 v[120:123], v[92:95], v[128:131], v[120:123]
	v_mfma_i32_16x16x64_i8 v[116:119], v[92:95], v[140:143], v[116:119]
	v_mfma_i32_16x16x64_i8 v[124:127], v[84:87], v[140:143], v[124:127]
	v_mfma_i32_16x16x64_i8 v[112:115], v[84:87], v[192:195], v[112:115]
	v_mfma_i32_16x16x64_i8 v[108:111], v[92:95], v[192:195], v[108:111]
	v_mfma_i32_16x16x64_i8 v[96:99], v[92:95], v[216:219], v[96:99]
	v_mfma_i32_16x16x64_i8 v[104:107], v[84:87], v[216:219], v[104:107]
	v_mfma_i32_16x16x64_i8 v[136:139], v[88:91], v[132:135], v[136:139]
	v_mfma_i32_16x16x64_i8 v[120:123], v[100:103], v[132:135], v[120:123]
	v_mfma_i32_16x16x64_i8 v[116:119], v[100:103], v[188:191], v[116:119]
	v_mfma_i32_16x16x64_i8 v[132:135], v[88:91], v[188:191], v[124:127]
	v_mfma_i32_16x16x64_i8 v[112:115], v[88:91], v[196:199], v[112:115]
	v_mfma_i32_16x16x64_i8 v[108:111], v[100:103], v[196:199], v[108:111]
	v_mfma_i32_16x16x64_i8 v[96:99], v[100:103], v[220:223], v[96:99]
	v_mfma_i32_16x16x64_i8 v[104:107], v[88:91], v[220:223], v[104:107]
	s_barrier
	s_add_i32 s8, s10, s12
	s_add_u32 s98, s82, 0x80
	s_addc_u32 s99, s83, 0
	s_add_u32 s100, vcc_lo, 0x80
	s_addc_u32 s101, vcc_hi, 0
	s_mov_b32 m0, s8
	ds_read_b128 v[124:127], v215 offset:49152
	ds_read_b128 v[128:131], v215 offset:50176
	ds_read_b128 v[140:143], v215 offset:51200
	ds_read_b128 v[188:191], v215 offset:52224
	ds_read_b128 v[192:195], v215 offset:53248
	ds_read_b128 v[196:199], v215 offset:54272
	ds_read_b128 v[216:219], v215 offset:55296
	ds_read_b128 v[220:223], v215 offset:56320
	global_load_lds_dwordx4 v178, s[98:99]
	s_add_i32 m0, s8, 0x2000
	s_add_u32 s8, s82, 0x40080
	s_addc_u32 s9, s83, 0
	s_add_i32 s10, s11, s12
	global_load_lds_dwordx4 v182, s[98:99]
	s_mov_b32 m0, s10
	s_nop 0
	global_load_lds_dwordx4 v178, s[8:9]
	s_add_i32 m0, s10, 0x2000
	s_nop 0
	global_load_lds_dwordx4 v182, s[8:9]
	s_mov_b32 m0, s58
	s_nop 0
	global_load_lds_dwordx4 v176, s[100:101]
	s_mov_b32 m0, s4
	s_nop 0
	global_load_lds_dwordx4 v180, s[100:101]
	s_waitcnt vmcnt(8)
	s_waitcnt lgkmcnt(0)
	s_barrier
	s_waitcnt lgkmcnt(0)
	v_mfma_i32_16x16x64_i8 v[80:83], v[44:47], v[124:127], v[80:83]
	v_mfma_i32_16x16x64_i8 v[72:75], v[60:63], v[124:127], v[72:75]
	v_mfma_i32_16x16x64_i8 v[68:71], v[60:63], v[140:143], v[68:71]
	v_mfma_i32_16x16x64_i8 v[76:79], v[44:47], v[140:143], v[76:79]
	v_mfma_i32_16x16x64_i8 v[56:59], v[44:47], v[192:195], v[56:59]
	v_mfma_i32_16x16x64_i8 v[48:51], v[60:63], v[192:195], v[48:51]
	v_mfma_i32_16x16x64_i8 v[36:39], v[60:63], v[216:219], v[36:39]
	v_mfma_i32_16x16x64_i8 v[40:43], v[44:47], v[216:219], v[40:43]
	v_mfma_i32_16x16x64_i8 v[80:83], v[52:55], v[128:131], v[80:83]
	v_mfma_i32_16x16x64_i8 v[72:75], v[64:67], v[128:131], v[72:75]
	v_mfma_i32_16x16x64_i8 v[68:71], v[64:67], v[188:191], v[68:71]
	v_mfma_i32_16x16x64_i8 v[76:79], v[52:55], v[188:191], v[76:79]
	v_mfma_i32_16x16x64_i8 v[56:59], v[52:55], v[196:199], v[56:59]
	v_mfma_i32_16x16x64_i8 v[48:51], v[64:67], v[196:199], v[48:51]
	v_mfma_i32_16x16x64_i8 v[36:39], v[64:67], v[220:223], v[36:39]
	v_mfma_i32_16x16x64_i8 v[40:43], v[52:55], v[220:223], v[40:43]
	v_mfma_i32_16x16x64_i8 v[32:35], v[84:87], v[124:127], v[32:35]
	v_mfma_i32_16x16x64_i8 v[24:27], v[92:95], v[124:127], v[24:27]
	v_mfma_i32_16x16x64_i8 v[20:23], v[92:95], v[140:143], v[20:23]
	v_mfma_i32_16x16x64_i8 v[28:31], v[84:87], v[140:143], v[28:31]
	v_mfma_i32_16x16x64_i8 v[16:19], v[84:87], v[192:195], v[16:19]
	v_mfma_i32_16x16x64_i8 v[12:15], v[92:95], v[192:195], v[12:15]
	v_mfma_i32_16x16x64_i8 v[2:5], v[92:95], v[216:219], v[2:5]
	v_mfma_i32_16x16x64_i8 v[6:9], v[84:87], v[216:219], v[8:11]
	v_mfma_i32_16x16x64_i8 v[32:35], v[88:91], v[128:131], v[32:35]
	v_mfma_i32_16x16x64_i8 v[24:27], v[100:103], v[128:131], v[24:27]
	v_mfma_i32_16x16x64_i8 v[20:23], v[100:103], v[188:191], v[20:23]
	v_mfma_i32_16x16x64_i8 v[28:31], v[88:91], v[188:191], v[28:31]
	v_mfma_i32_16x16x64_i8 v[16:19], v[88:91], v[196:199], v[16:19]
	v_mfma_i32_16x16x64_i8 v[12:15], v[100:103], v[196:199], v[12:15]
	v_mfma_i32_16x16x64_i8 v[8:11], v[88:91], v[220:223], v[6:9]
	v_mfma_i32_16x16x64_i8 v[4:7], v[100:103], v[220:223], v[2:5]
	s_barrier
	s_add_i32 s5, s5, 2
	s_add_u32 s85, s85, 0x100
	s_addc_u32 s68, s68, 0
	s_cmp_gt_u32 s5, 13
	s_mov_b64 s[8:9], s[70:71]
	s_cbranch_scc0 .LBB0_385
